# GEMM k-loops: stage-release barrier placed after the first 16 MFMAs; loads of k-step k+2 issued mid k-step
# baseline (speedup 1.0000x reference)
.LBB0_231:
	s_add_i32 s47, s48, 0x8000
	s_and_b32 s27, s48, 0x8000
	s_and_b32 s50, s47, 0x8000
	s_add_i32 s48, s27, 0
	s_add_i32 s27, s50, 0
	s_add_u32 s70, s48, s71
	s_waitcnt vmcnt(8)
	s_barrier
	v_add3_u32 v145, s48, v86, v87
	v_add3_u32 v208, s48, v87, v88
	v_add3_u32 v209, s48, v86, v89
	v_add3_u32 v210, s48, v88, v89
	ds_read_b128 v[104:107], v208
	ds_read_b128 v[100:103], v145 offset:16384
	ds_read_b128 v[108:111], v145 offset:18432
	ds_read_b128 v[164:167], v208 offset:2048
	ds_read_b128 v[112:115], v145 offset:20480
	ds_read_b128 v[116:119], v145 offset:22528
	ds_read_b128 v[120:123], v145 offset:24576
	ds_read_b128 v[124:127], v145 offset:26624
	ds_read_b128 v[128:131], v145 offset:28672
	ds_read_b128 v[132:135], v145 offset:30720
	ds_read_b128 v[200:203], v210
	ds_read_b128 v[168:171], v209 offset:16384
	ds_read_b128 v[172:175], v209 offset:18432
	ds_read_b128 v[204:207], v210 offset:2048
	ds_read_b128 v[176:179], v209 offset:20480
	ds_read_b128 v[180:183], v209 offset:22528
	ds_read_b128 v[184:187], v209 offset:24576
	ds_read_b128 v[188:191], v209 offset:26624
	ds_read_b128 v[192:195], v209 offset:28672
	ds_read_b128 v[196:199], v209 offset:30720
	s_waitcnt lgkmcnt(15)
	v_mfma_f32_16x16x32_bf16 v[60:63], v[100:103], v[104:107], v[60:63]
	v_mfma_f32_16x16x32_bf16 v[56:59], v[108:111], v[104:107], v[56:59]
	v_mfma_f32_16x16x32_bf16 v[24:27], v[100:103], v[164:167], v[24:27]
	v_mfma_f32_16x16x32_bf16 v[20:23], v[108:111], v[164:167], v[20:23]
	v_mfma_f32_16x16x32_bf16 v[52:55], v[112:115], v[104:107], v[52:55]
	v_mfma_f32_16x16x32_bf16 v[16:19], v[112:115], v[164:167], v[16:19]
	s_waitcnt lgkmcnt(14)
	v_mfma_f32_16x16x32_bf16 v[48:51], v[116:119], v[104:107], v[48:51]
	v_mfma_f32_16x16x32_bf16 v[12:15], v[116:119], v[164:167], v[12:15]
	s_waitcnt lgkmcnt(13)
	v_mfma_f32_16x16x32_bf16 v[44:47], v[120:123], v[104:107], v[44:47]
	v_mfma_f32_16x16x32_bf16 v[8:11], v[120:123], v[164:167], v[8:11]
	s_waitcnt lgkmcnt(12)
	v_mfma_f32_16x16x32_bf16 v[40:43], v[124:127], v[104:107], v[40:43]
	v_mfma_f32_16x16x32_bf16 v[4:7], v[124:127], v[164:167], v[4:7]
	s_waitcnt lgkmcnt(11)
	v_mfma_f32_16x16x32_bf16 v[36:39], v[128:131], v[104:107], v[36:39]
	v_mfma_f32_16x16x32_bf16 v[0:3], v[128:131], v[164:167], v[0:3]
	s_waitcnt lgkmcnt(10)
	v_mfma_f32_16x16x32_bf16 v[32:35], v[132:135], v[104:107], v[32:35]
	v_mfma_f32_16x16x32_bf16 v[28:31], v[132:135], v[164:167], v[28:31]
	s_waitcnt lgkmcnt(0)
	s_barrier
	s_cmpk_eq_i32 s24, 0x700
	s_cbranch_scc1 .Lgskip_231
	s_mov_b32 m0, s70
	s_nop 0
	global_load_lds_dwordx4 v244, s[96:97]
	s_add_u32 m0, s70, 0x4000
	s_nop 0
	global_load_lds_dwordx4 v245, s[72:73]
	s_add_u32 m0, s70, 0x1000
	s_nop 0
	global_load_lds_dwordx4 v246, s[96:97]
	s_add_u32 m0, s70, 0x5000
	s_nop 0
	global_load_lds_dwordx4 v247, s[72:73]
	s_add_u32 m0, s70, 0x2000
	s_nop 0
	global_load_lds_dwordx4 v248, s[96:97]
	s_add_u32 m0, s70, 0x6000
	s_nop 0
	global_load_lds_dwordx4 v249, s[72:73]
	s_add_u32 m0, s70, 0x3000
	s_nop 0
	global_load_lds_dwordx4 v250, s[96:97]
	s_add_u32 m0, s70, 0x7000
	s_nop 0
	global_load_lds_dwordx4 v251, s[72:73]
	s_add_u32 s96, s96, 0x80
	s_addc_u32 s97, s97, 0
	s_add_u32 s72, s72, 0x80
	s_addc_u32 s73, s73, 0
.Lgskip_231:
	s_add_u32 s24, s24, 0x80
	s_addc_u32 s25, s25, 0
	s_cmpk_eq_i32 s24, 0x780
	s_mov_b32 s48, s47
	v_mfma_f32_16x16x32_bf16 v[60:63], v[168:171], v[200:203], v[60:63]
	v_mfma_f32_16x16x32_bf16 v[56:59], v[172:175], v[200:203], v[56:59]
	v_mfma_f32_16x16x32_bf16 v[24:27], v[168:171], v[204:207], v[24:27]
	v_mfma_f32_16x16x32_bf16 v[20:23], v[172:175], v[204:207], v[20:23]
	v_mfma_f32_16x16x32_bf16 v[52:55], v[176:179], v[200:203], v[52:55]
	v_mfma_f32_16x16x32_bf16 v[16:19], v[176:179], v[204:207], v[16:19]
	v_mfma_f32_16x16x32_bf16 v[48:51], v[180:183], v[200:203], v[48:51]
	v_mfma_f32_16x16x32_bf16 v[12:15], v[180:183], v[204:207], v[12:15]
	v_mfma_f32_16x16x32_bf16 v[44:47], v[184:187], v[200:203], v[44:47]
	v_mfma_f32_16x16x32_bf16 v[8:11], v[184:187], v[204:207], v[8:11]
	v_mfma_f32_16x16x32_bf16 v[40:43], v[188:191], v[200:203], v[40:43]
	v_mfma_f32_16x16x32_bf16 v[4:7], v[188:191], v[204:207], v[4:7]
	v_mfma_f32_16x16x32_bf16 v[36:39], v[192:195], v[200:203], v[36:39]
	v_mfma_f32_16x16x32_bf16 v[0:3], v[192:195], v[204:207], v[0:3]
	v_mfma_f32_16x16x32_bf16 v[32:35], v[196:199], v[200:203], v[32:35]
	v_mfma_f32_16x16x32_bf16 v[28:31], v[196:199], v[204:207], v[28:31]
	s_cbranch_scc0 .LBB0_231
	v_add_u32_e32 v64, s27, v86
	v_add_u32_e32 v136, v64, v87
	v_add3_u32 v108, s27, v87, v88
	s_waitcnt vmcnt(0)
	s_barrier
	ds_read_b128 v[80:83], v136 offset:16384
	ds_read_b128 v[100:103], v136 offset:18432
	ds_read_b128 v[104:107], v108
	ds_read_b128 v[108:111], v108 offset:2048
	ds_read_b128 v[112:115], v136 offset:20480
	ds_read_b128 v[116:119], v136 offset:22528
	ds_read_b128 v[128:131], v136 offset:28672
	s_waitcnt lgkmcnt(2)
	v_mfma_f32_16x16x32_bf16 v[120:123], v[112:115], v[104:107], v[52:55]
	s_nop 2
	ds_read_b128 v[52:55], v136 offset:24576
	ds_read_b128 v[124:127], v136 offset:26624
	s_cmp_gt_i32 s26, 11
	s_waitcnt lgkmcnt(0)
	v_mfma_f32_16x16x32_bf16 v[132:135], v[124:127], v[104:107], v[40:43]
	s_nop 2
	ds_read_b128 v[40:43], v136 offset:30720
	s_cselect_b64 s[24:25], -1, 0
	s_cmp_lt_i32 s26, 12
	v_mfma_f32_16x16x32_bf16 v[60:63], v[80:83], v[104:107], v[60:63]
	s_cselect_b64 s[48:49], -1, 0
	v_mfma_f32_16x16x32_bf16 v[56:59], v[100:103], v[104:107], v[56:59]
	v_mfma_f32_16x16x32_bf16 v[48:51], v[116:119], v[104:107], v[48:51]
	v_mfma_f32_16x16x32_bf16 v[44:47], v[52:55], v[104:107], v[44:47]
	v_mfma_f32_16x16x32_bf16 v[136:139], v[128:131], v[104:107], v[36:39]
	s_waitcnt lgkmcnt(0)
	v_mfma_f32_16x16x32_bf16 v[32:35], v[40:43], v[104:107], v[32:35]
	v_mfma_f32_16x16x32_bf16 v[104:107], v[52:55], v[108:111], v[8:11]
	s_nop 2
	v_add_u32_e32 v8, v64, v89
	v_mfma_f32_16x16x32_bf16 v[24:27], v[80:83], v[108:111], v[24:27]
	v_add3_u32 v9, s27, v89, v88
	v_lshl_or_b32 v64, s26, 7, v90
	s_sub_i32 s26, s26, 18
	v_mfma_f32_16x16x32_bf16 v[80:83], v[112:115], v[108:111], v[16:19]
	s_cmp_lt_u32 s26, 8
	s_cselect_b64 s[26:27], -1, 0
	s_or_b64 s[48:49], s[48:49], s[26:27]
	v_mfma_f32_16x16x32_bf16 v[112:115], v[124:127], v[108:111], v[4:7]
	s_mov_b64 s[26:27], -1
	s_andn2_b64 vcc, exec, s[48:49]
	s_nop 0
	ds_read_b128 v[4:7], v8 offset:16384
	v_mfma_f32_16x16x32_bf16 v[20:23], v[100:103], v[108:111], v[20:23]
	v_mfma_f32_16x16x32_bf16 v[100:103], v[116:119], v[108:111], v[12:15]
	v_mfma_f32_16x16x32_bf16 v[116:119], v[128:131], v[108:111], v[0:3]
	ds_read_b128 v[124:127], v8 offset:18432
	s_nop 1
	ds_read_b128 v[0:3], v9
	ds_read_b128 v[128:131], v9 offset:2048
	ds_read_b128 v[140:143], v8 offset:22528
	ds_read_b128 v[146:149], v8 offset:28672
	s_waitcnt lgkmcnt(3)
	v_mfma_f32_16x16x32_bf16 v[52:55], v[4:7], v[0:3], v[60:63]
	s_nop 2
	ds_read_b128 v[60:63], v8 offset:20480
	v_mfma_f32_16x16x32_bf16 v[108:111], v[40:43], v[108:111], v[28:31]
	s_waitcnt lgkmcnt(0)
	v_mfma_f32_16x16x32_bf16 v[36:39], v[60:63], v[0:3], v[120:123]
	s_nop 2
	ds_read_b128 v[120:123], v8 offset:24576
	v_mfma_f32_16x16x32_bf16 v[40:43], v[140:143], v[0:3], v[48:51]
	s_nop 2
	ds_read_b128 v[48:51], v8 offset:26624
	s_waitcnt lgkmcnt(0)
	v_mfma_f32_16x16x32_bf16 v[16:19], v[48:51], v[0:3], v[132:135]
	s_nop 2
	ds_read_b128 v[132:135], v8 offset:30720
	v_mfma_f32_16x16x32_bf16 v[56:59], v[124:127], v[0:3], v[56:59]
	v_mfma_f32_16x16x32_bf16 v[12:15], v[120:123], v[0:3], v[44:47]
	v_mfma_f32_16x16x32_bf16 v[8:11], v[146:149], v[0:3], v[136:139]
	s_waitcnt lgkmcnt(0)
	v_mfma_f32_16x16x32_bf16 v[0:3], v[132:135], v[0:3], v[32:35]
	v_mfma_f32_16x16x32_bf16 v[28:31], v[4:7], v[128:131], v[24:27]
	v_mfma_f32_16x16x32_bf16 v[20:23], v[124:127], v[128:131], v[20:23]
	v_mfma_f32_16x16x32_bf16 v[4:7], v[60:63], v[128:131], v[80:83]
	v_mfma_f32_16x16x32_bf16 v[24:27], v[140:143], v[128:131], v[100:103]
	s_nop 1
	v_lshl_add_u32 v80, s46, 7, v85
	v_mfma_f32_16x16x32_bf16 v[32:35], v[120:123], v[128:131], v[104:107]
	v_mfma_f32_16x16x32_bf16 v[44:47], v[48:51], v[128:131], v[112:115]
	v_mfma_f32_16x16x32_bf16 v[48:51], v[146:149], v[128:131], v[116:119]
	v_mfma_f32_16x16x32_bf16 v[60:63], v[132:135], v[128:131], v[108:111]
	s_cbranch_vccz .LBB0_240
	s_and_b32 s47, 0xffff, s45
	s_cmp_gt_u32 s47, 17
	s_cbranch_scc0 .LBB0_237
	s_cmp_eq_u32 s47, 26
	s_cselect_b64 s[26:27], -1, 0
	s_and_b64 s[48:49], s[10:11], s[26:27]
	s_and_saveexec_b64 s[26:27], s[48:49]
	s_cbranch_execz .LBB0_236
	global_load_dwordx4 v[100:103], v[72:73], off
	v_mad_i64_i32 v[82:83], s[48:49], v80, s28, v[70:71]
	v_or_b32_e32 v81, 16, v80
	s_waitcnt vmcnt(0)
	v_pk_add_f32 v[102:103], v[54:55], v[102:103]
	v_pk_add_f32 v[100:101], v[52:53], v[100:101]
	global_store_dwordx4 v[82:83], v[100:103], off
	global_load_dwordx4 v[100:103], v[72:73], off offset:16
	v_mad_i64_i32 v[82:83], s[48:49], v80, s28, v[74:75]
	s_waitcnt vmcnt(0)
	v_pk_add_f32 v[102:103], v[58:59], v[102:103]
	v_pk_add_f32 v[100:101], v[56:57], v[100:101]
	global_store_dwordx4 v[82:83], v[100:103], off
	global_load_dwordx4 v[100:103], v[72:73], off
	v_mad_i64_i32 v[82:83], s[48:49], v81, s28, v[70:71]
	s_waitcnt vmcnt(0)
	v_pk_add_f32 v[102:103], v[30:31], v[102:103]
	v_pk_add_f32 v[100:101], v[28:29], v[100:101]
	global_store_dwordx4 v[82:83], v[100:103], off
	global_load_dwordx4 v[100:103], v[72:73], off offset:16
	v_mad_i64_i32 v[82:83], s[48:49], v81, s28, v[74:75]
	s_waitcnt vmcnt(0)
	v_pk_add_f32 v[102:103], v[22:23], v[102:103]
	v_pk_add_f32 v[100:101], v[20:21], v[100:101]
	global_store_dwordx4 v[82:83], v[100:103], off

.LBB0_855:
	s_add_i32 s45, s43, 0x8000
	s_and_b32 s44, s45, 0x8000
	s_add_i32 s44, s44, 0
	s_and_b32 s43, s43, 0x8000
	s_add_i32 s43, s43, 0
	s_add_u32 s86, s43, s87
	s_waitcnt vmcnt(8)
	s_barrier
	v_add3_u32 v212, s43, v88, v89
	v_add3_u32 v213, s43, v89, v90
	v_add3_u32 v214, s43, v88, v91
	v_add3_u32 v215, s43, v90, v91
	ds_read_b128 v[106:109], v213
	ds_read_b128 v[76:79], v212 offset:16384
	ds_read_b128 v[102:105], v212 offset:18432
	ds_read_b128 v[110:113], v213 offset:2048
	ds_read_b128 v[114:117], v212 offset:20480
	ds_read_b128 v[118:121], v212 offset:22528
	ds_read_b128 v[122:125], v212 offset:24576
	ds_read_b128 v[126:129], v212 offset:26624
	ds_read_b128 v[130:133], v212 offset:28672
	ds_read_b128 v[134:137], v212 offset:30720
	ds_read_b128 v[180:183], v215
	ds_read_b128 v[172:175], v214 offset:16384
	ds_read_b128 v[176:179], v214 offset:18432
	ds_read_b128 v[184:187], v215 offset:2048
	ds_read_b128 v[188:191], v214 offset:20480
	ds_read_b128 v[192:195], v214 offset:22528
	ds_read_b128 v[196:199], v214 offset:24576
	ds_read_b128 v[200:203], v214 offset:26624
	ds_read_b128 v[204:207], v214 offset:28672
	ds_read_b128 v[208:211], v214 offset:30720
	s_waitcnt lgkmcnt(15)
	v_mfma_f32_16x16x32_bf16 v[60:63], v[76:79], v[106:109], v[60:63]
	v_mfma_f32_16x16x32_bf16 v[56:59], v[102:105], v[106:109], v[56:59]
	v_mfma_f32_16x16x32_bf16 v[24:27], v[76:79], v[110:113], v[24:27]
	v_mfma_f32_16x16x32_bf16 v[20:23], v[102:105], v[110:113], v[20:23]
	v_mfma_f32_16x16x32_bf16 v[52:55], v[114:117], v[106:109], v[52:55]
	v_mfma_f32_16x16x32_bf16 v[16:19], v[114:117], v[110:113], v[16:19]
	s_waitcnt lgkmcnt(14)
	v_mfma_f32_16x16x32_bf16 v[48:51], v[118:121], v[106:109], v[48:51]
	v_mfma_f32_16x16x32_bf16 v[12:15], v[118:121], v[110:113], v[12:15]
	s_waitcnt lgkmcnt(13)
	v_mfma_f32_16x16x32_bf16 v[44:47], v[122:125], v[106:109], v[44:47]
	v_mfma_f32_16x16x32_bf16 v[8:11], v[122:125], v[110:113], v[8:11]
	s_waitcnt lgkmcnt(12)
	v_mfma_f32_16x16x32_bf16 v[40:43], v[126:129], v[106:109], v[40:43]
	v_mfma_f32_16x16x32_bf16 v[4:7], v[126:129], v[110:113], v[4:7]
	s_waitcnt lgkmcnt(11)
	v_mfma_f32_16x16x32_bf16 v[32:35], v[130:133], v[106:109], v[32:35]
	v_mfma_f32_16x16x32_bf16 v[0:3], v[130:133], v[110:113], v[0:3]
	s_waitcnt lgkmcnt(10)
	v_mfma_f32_16x16x32_bf16 v[28:31], v[134:137], v[106:109], v[28:31]
	v_mfma_f32_16x16x32_bf16 v[36:39], v[134:137], v[110:113], v[36:39]
	s_waitcnt lgkmcnt(0)
	s_barrier
	s_cmpk_eq_i32 s34, 0x700
	s_cbranch_scc1 .Lgskip_855
	s_mov_b32 m0, s86
	s_nop 0
	global_load_lds_dwordx4 v244, s[96:97]
	s_add_u32 m0, s86, 0x4000
	s_nop 0
	global_load_lds_dwordx4 v245, s[88:89]
	s_add_u32 m0, s86, 0x1000
	s_nop 0
	global_load_lds_dwordx4 v246, s[96:97]
	s_add_u32 m0, s86, 0x5000
	s_nop 0
	global_load_lds_dwordx4 v247, s[88:89]
	s_add_u32 m0, s86, 0x2000
	s_nop 0
	global_load_lds_dwordx4 v248, s[96:97]
	s_add_u32 m0, s86, 0x6000
	s_nop 0
	global_load_lds_dwordx4 v249, s[88:89]
	s_add_u32 m0, s86, 0x3000
	s_nop 0
	global_load_lds_dwordx4 v250, s[96:97]
	s_add_u32 m0, s86, 0x7000
	s_nop 0
	global_load_lds_dwordx4 v251, s[88:89]
	s_add_u32 s96, s96, 0x80
	s_addc_u32 s97, s97, 0
	s_add_u32 s88, s88, 0x80
	s_addc_u32 s89, s89, 0
.Lgskip_855:
	s_add_u32 s34, s34, 0x80
	s_addc_u32 s35, s35, 0
	s_cmpk_eq_i32 s34, 0x780
	s_mov_b32 s43, s45
	v_mfma_f32_16x16x32_bf16 v[60:63], v[172:175], v[180:183], v[60:63]
	v_mfma_f32_16x16x32_bf16 v[56:59], v[176:179], v[180:183], v[56:59]
	v_mfma_f32_16x16x32_bf16 v[24:27], v[172:175], v[184:187], v[24:27]
	v_mfma_f32_16x16x32_bf16 v[20:23], v[176:179], v[184:187], v[20:23]
	v_mfma_f32_16x16x32_bf16 v[52:55], v[188:191], v[180:183], v[52:55]
	v_mfma_f32_16x16x32_bf16 v[16:19], v[188:191], v[184:187], v[16:19]
	v_mfma_f32_16x16x32_bf16 v[48:51], v[192:195], v[180:183], v[48:51]
	v_mfma_f32_16x16x32_bf16 v[12:15], v[192:195], v[184:187], v[12:15]
	v_mfma_f32_16x16x32_bf16 v[44:47], v[196:199], v[180:183], v[44:47]
	v_mfma_f32_16x16x32_bf16 v[8:11], v[196:199], v[184:187], v[8:11]
	v_mfma_f32_16x16x32_bf16 v[40:43], v[200:203], v[180:183], v[40:43]
	v_mfma_f32_16x16x32_bf16 v[4:7], v[200:203], v[184:187], v[4:7]
	v_mfma_f32_16x16x32_bf16 v[32:35], v[204:207], v[180:183], v[32:35]
	v_mfma_f32_16x16x32_bf16 v[0:3], v[204:207], v[184:187], v[0:3]
	v_mfma_f32_16x16x32_bf16 v[28:31], v[208:211], v[180:183], v[28:31]
	v_mfma_f32_16x16x32_bf16 v[36:39], v[208:211], v[184:187], v[36:39]
	s_cbranch_scc0 .LBB0_855
	v_add_u32_e32 v80, s44, v88
	v_add_u32_e32 v81, v80, v89
	v_add3_u32 v106, s44, v89, v90
	s_waitcnt vmcnt(0)
	s_barrier
	ds_read_b128 v[72:75], v81 offset:16384
	ds_read_b128 v[76:79], v81 offset:18432
	ds_read_b128 v[102:105], v106
	ds_read_b128 v[106:109], v106 offset:2048
	ds_read_b128 v[110:113], v81 offset:20480
	ds_read_b128 v[114:117], v81 offset:22528
	ds_read_b128 v[118:121], v81 offset:24576
	ds_read_b128 v[122:125], v81 offset:26624
	ds_read_b128 v[126:129], v81 offset:28672
	ds_read_b128 v[130:133], v81 offset:30720
	v_add_u32_e32 v80, v80, v91
	s_waitcnt lgkmcnt(7)
	v_mfma_f32_16x16x32_bf16 v[60:63], v[72:75], v[102:105], v[60:63]
	s_lshl_b32 s42, s42, 7
	v_mfma_f32_16x16x32_bf16 v[56:59], v[76:79], v[102:105], v[56:59]
	s_waitcnt lgkmcnt(4)
	v_mfma_f32_16x16x32_bf16 v[48:51], v[114:117], v[102:105], v[48:51]
	s_waitcnt lgkmcnt(3)
	v_mfma_f32_16x16x32_bf16 v[44:47], v[118:121], v[102:105], v[44:47]
	s_waitcnt lgkmcnt(2)
	v_mfma_f32_16x16x32_bf16 v[40:43], v[122:125], v[102:105], v[40:43]
	s_waitcnt lgkmcnt(1)
	v_mfma_f32_16x16x32_bf16 v[32:35], v[126:129], v[102:105], v[32:35]
	s_waitcnt lgkmcnt(0)
	v_mfma_f32_16x16x32_bf16 v[28:31], v[130:133], v[102:105], v[28:31]
	v_mfma_f32_16x16x32_bf16 v[24:27], v[72:75], v[106:109], v[24:27]
	ds_read_b128 v[72:75], v80 offset:16384
	v_mfma_f32_16x16x32_bf16 v[52:55], v[110:113], v[102:105], v[52:55]
	v_mfma_f32_16x16x32_bf16 v[20:23], v[76:79], v[106:109], v[20:23]
	v_mfma_f32_16x16x32_bf16 v[16:19], v[110:113], v[106:109], v[16:19]
	v_mfma_f32_16x16x32_bf16 v[12:15], v[114:117], v[106:109], v[12:15]
	v_mfma_f32_16x16x32_bf16 v[8:11], v[118:121], v[106:109], v[8:11]
	v_mfma_f32_16x16x32_bf16 v[4:7], v[122:125], v[106:109], v[4:7]
	v_mfma_f32_16x16x32_bf16 v[0:3], v[126:129], v[106:109], v[0:3]
	v_mfma_f32_16x16x32_bf16 v[102:105], v[130:133], v[106:109], v[36:39]
	s_nop 2
	v_add3_u32 v36, s44, v91, v90
	ds_read_b128 v[76:79], v80 offset:18432
	ds_read_b128 v[106:109], v36
	ds_read_b128 v[110:113], v36 offset:2048
	ds_read_b128 v[130:133], v80 offset:28672
	ds_read_b128 v[134:137], v80 offset:30720
	ds_read_b128 v[114:117], v80 offset:20480
	ds_read_b128 v[118:121], v80 offset:22528
	ds_read_b128 v[122:125], v80 offset:24576
	ds_read_b128 v[126:129], v80 offset:26624
	s_waitcnt lgkmcnt(7)
	v_mfma_f32_16x16x32_bf16 v[60:63], v[72:75], v[106:109], v[60:63]
	v_readlane_b32 s44, v252, 5
	v_readlane_b32 s48, v252, 9
	v_readlane_b32 s49, v252, 10
	s_waitcnt lgkmcnt(5)
	v_mfma_f32_16x16x32_bf16 v[36:39], v[130:133], v[106:109], v[32:35]
	v_readlane_b32 s45, v252, 6
	v_readlane_b32 s46, v252, 7
	v_readlane_b32 s47, v252, 8
	s_waitcnt lgkmcnt(4)
	v_mfma_f32_16x16x32_bf16 v[32:35], v[134:137], v[106:109], v[28:31]
	v_readlane_b32 s50, v252, 11
	v_readlane_b32 s51, v252, 12
	v_readlane_b32 s52, v252, 13
	v_mfma_f32_16x16x32_bf16 v[28:31], v[72:75], v[110:113], v[24:27]
	v_add_u32_e32 v72, s42, v82
	v_mul_hi_i32 v73, v72, s36
	v_lshrrev_b32_e32 v74, 31, v73
	v_mfma_f32_16x16x32_bf16 v[24:27], v[76:79], v[110:113], v[20:23]
	v_readlane_b32 s53, v252, 14
	v_readlane_b32 s54, v252, 15
	v_readlane_b32 s55, v252, 16
	s_waitcnt lgkmcnt(3)
	v_mfma_f32_16x16x32_bf16 v[20:23], v[114:117], v[110:113], v[16:19]
	v_readlane_b32 s56, v252, 17
	v_readlane_b32 s57, v252, 18
	v_readlane_b32 s58, v252, 19
	s_waitcnt lgkmcnt(2)
	v_mfma_f32_16x16x32_bf16 v[16:19], v[118:121], v[110:113], v[12:15]
	v_readlane_b32 s59, v252, 20
	s_waitcnt lgkmcnt(1)
	v_mfma_f32_16x16x32_bf16 v[12:15], v[122:125], v[110:113], v[8:11]
	s_waitcnt lgkmcnt(0)
	v_mfma_f32_16x16x32_bf16 v[8:11], v[126:129], v[110:113], v[4:7]
	s_nop 2
	v_ashrrev_i32_e32 v4, 11, v73
	v_mfma_f32_16x16x32_bf16 v[56:59], v[76:79], v[106:109], v[56:59]
	v_add_u32_e32 v73, v4, v74
	v_mad_i32_i24 v75, v73, s37, v72
	v_lshlrev_b32_e32 v78, 13, v73
	v_mfma_f32_16x16x32_bf16 v[52:55], v[114:117], v[106:109], v[52:55]
	v_cmp_lt_i32_e32 vcc, s38, v75
	v_mov_b64_e32 v[76:77], s[48:49]
	v_add3_u32 v74, v78, v75, s39
	v_mfma_f32_16x16x32_bf16 v[48:51], v[118:121], v[106:109], v[48:51]
	v_mfma_f32_16x16x32_bf16 v[44:47], v[122:125], v[106:109], v[44:47]
	v_mfma_f32_16x16x32_bf16 v[40:43], v[126:129], v[106:109], v[40:43]
	v_mfma_f32_16x16x32_bf16 v[0:3], v[130:133], v[110:113], v[0:3]
	v_mfma_f32_16x16x32_bf16 v[4:7], v[134:137], v[110:113], v[102:105]
	s_and_saveexec_b64 s[34:35], vcc
	s_xor_b64 s[34:35], exec, s[34:35]
	s_cbranch_execz .LBB0_858
	v_readlane_b32 s44, v252, 5
	v_readlane_b32 s45, v252, 6
	v_add3_u32 v72, v78, v75, s39
	v_readlane_b32 s46, v252, 7
	v_readlane_b32 s47, v252, 8
	v_readlane_b32 s48, v252, 9
	v_readlane_b32 s49, v252, 10
	v_readlane_b32 s50, v252, 11
	v_readlane_b32 s51, v252, 12
	v_readlane_b32 s52, v252, 13
	v_readlane_b32 s53, v252, 14
	v_readlane_b32 s54, v252, 15
	v_readlane_b32 s55, v252, 16
	v_readlane_b32 s56, v252, 17
	v_readlane_b32 s57, v252, 18
	v_readlane_b32 s58, v252, 19
	v_readlane_b32 s59, v252, 20
	v_mov_b64_e32 v[76:77], s[44:45]
	s_or_saveexec_b64 s[34:35], s[34:35]
	v_lshl_add_u32 v102, v73, 8, v75
	s_xor_b64 exec, exec, s[34:35]
	s_branch .LBB0_859

.LBB0_1006:
	s_add_i32 s37, s35, 0x8000
	s_and_b32 s36, s37, 0x8000
	s_add_i32 s36, s36, 0
	s_and_b32 s35, s35, 0x8000
	s_add_i32 s35, s35, 0
	s_add_u32 s86, s35, s87
	s_waitcnt vmcnt(8)
	s_barrier
	v_add3_u32 v143, s35, v80, v81
	v_add3_u32 v145, s35, v81, v82
	v_add3_u32 v206, s35, v80, v83
	v_add3_u32 v207, s35, v82, v83
	ds_read_b128 v[102:105], v145
	ds_read_b128 v[94:97], v143 offset:16384
	ds_read_b128 v[98:101], v143 offset:18432
	ds_read_b128 v[106:109], v145 offset:2048
	ds_read_b128 v[110:113], v143 offset:20480
	ds_read_b128 v[114:117], v143 offset:22528
	ds_read_b128 v[118:121], v143 offset:24576
	ds_read_b128 v[122:125], v143 offset:26624
	ds_read_b128 v[126:129], v143 offset:28672
	ds_read_b128 v[130:133], v143 offset:30720
	ds_read_b128 v[174:177], v207
	ds_read_b128 v[166:169], v206 offset:16384
	ds_read_b128 v[170:173], v206 offset:18432
	ds_read_b128 v[178:181], v207 offset:2048
	ds_read_b128 v[182:185], v206 offset:20480
	ds_read_b128 v[186:189], v206 offset:22528
	ds_read_b128 v[190:193], v206 offset:24576
	ds_read_b128 v[194:197], v206 offset:26624
	ds_read_b128 v[198:201], v206 offset:28672
	ds_read_b128 v[202:205], v206 offset:30720
	s_waitcnt lgkmcnt(15)
	v_mfma_f32_16x16x32_bf16 v[60:63], v[94:97], v[102:105], v[60:63]
	v_mfma_f32_16x16x32_bf16 v[56:59], v[98:101], v[102:105], v[56:59]
	v_mfma_f32_16x16x32_bf16 v[28:31], v[94:97], v[106:109], v[28:31]
	v_mfma_f32_16x16x32_bf16 v[24:27], v[98:101], v[106:109], v[24:27]
	v_mfma_f32_16x16x32_bf16 v[52:55], v[110:113], v[102:105], v[52:55]
	v_mfma_f32_16x16x32_bf16 v[16:19], v[110:113], v[106:109], v[16:19]
	s_waitcnt lgkmcnt(14)
	v_mfma_f32_16x16x32_bf16 v[48:51], v[114:117], v[102:105], v[48:51]
	v_mfma_f32_16x16x32_bf16 v[12:15], v[114:117], v[106:109], v[12:15]
	s_waitcnt lgkmcnt(13)
	v_mfma_f32_16x16x32_bf16 v[44:47], v[118:121], v[102:105], v[44:47]
	v_mfma_f32_16x16x32_bf16 v[8:11], v[118:121], v[106:109], v[8:11]
	s_waitcnt lgkmcnt(12)
	v_mfma_f32_16x16x32_bf16 v[40:43], v[122:125], v[102:105], v[40:43]
	v_mfma_f32_16x16x32_bf16 v[4:7], v[122:125], v[106:109], v[4:7]
	s_waitcnt lgkmcnt(11)
	v_mfma_f32_16x16x32_bf16 v[36:39], v[126:129], v[102:105], v[36:39]
	v_mfma_f32_16x16x32_bf16 v[0:3], v[126:129], v[106:109], v[0:3]
	s_waitcnt lgkmcnt(10)
	v_mfma_f32_16x16x32_bf16 v[32:35], v[130:133], v[102:105], v[32:35]
	v_mfma_f32_16x16x32_bf16 v[20:23], v[130:133], v[106:109], v[20:23]
	s_waitcnt lgkmcnt(0)
	s_barrier
	s_cmpk_eq_i32 s26, 0x700
	s_cbranch_scc1 .Lgskip_1006
	s_mov_b32 m0, s86
	s_nop 0
	global_load_lds_dwordx4 v244, s[96:97]
	s_add_u32 m0, s86, 0x4000
	s_nop 0
	global_load_lds_dwordx4 v245, s[88:89]
	s_add_u32 m0, s86, 0x1000
	s_nop 0
	global_load_lds_dwordx4 v246, s[96:97]
	s_add_u32 m0, s86, 0x5000
	s_nop 0
	global_load_lds_dwordx4 v247, s[88:89]
	s_add_u32 m0, s86, 0x2000
	s_nop 0
	global_load_lds_dwordx4 v248, s[96:97]
	s_add_u32 m0, s86, 0x6000
	s_nop 0
	global_load_lds_dwordx4 v249, s[88:89]
	s_add_u32 m0, s86, 0x3000
	s_nop 0
	global_load_lds_dwordx4 v250, s[96:97]
	s_add_u32 m0, s86, 0x7000
	s_nop 0
	global_load_lds_dwordx4 v251, s[88:89]
	s_add_u32 s96, s96, 0x80
	s_addc_u32 s97, s97, 0
	s_add_u32 s88, s88, 0x80
	s_addc_u32 s89, s89, 0
.Lgskip_1006:
	s_add_u32 s26, s26, 0x80
	s_addc_u32 s27, s27, 0
	s_cmpk_eq_i32 s26, 0x780
	s_mov_b32 s35, s37
	v_mfma_f32_16x16x32_bf16 v[60:63], v[166:169], v[174:177], v[60:63]
	v_mfma_f32_16x16x32_bf16 v[56:59], v[170:173], v[174:177], v[56:59]
	v_mfma_f32_16x16x32_bf16 v[28:31], v[166:169], v[178:181], v[28:31]
	v_mfma_f32_16x16x32_bf16 v[24:27], v[170:173], v[178:181], v[24:27]
	v_mfma_f32_16x16x32_bf16 v[52:55], v[182:185], v[174:177], v[52:55]
	v_mfma_f32_16x16x32_bf16 v[16:19], v[182:185], v[178:181], v[16:19]
	v_mfma_f32_16x16x32_bf16 v[48:51], v[186:189], v[174:177], v[48:51]
	v_mfma_f32_16x16x32_bf16 v[12:15], v[186:189], v[178:181], v[12:15]
	v_mfma_f32_16x16x32_bf16 v[44:47], v[190:193], v[174:177], v[44:47]
	v_mfma_f32_16x16x32_bf16 v[8:11], v[190:193], v[178:181], v[8:11]
	v_mfma_f32_16x16x32_bf16 v[40:43], v[194:197], v[174:177], v[40:43]
	v_mfma_f32_16x16x32_bf16 v[4:7], v[194:197], v[178:181], v[4:7]
	v_mfma_f32_16x16x32_bf16 v[36:39], v[198:201], v[174:177], v[36:39]
	v_mfma_f32_16x16x32_bf16 v[0:3], v[198:201], v[178:181], v[0:3]
	v_mfma_f32_16x16x32_bf16 v[32:35], v[202:205], v[174:177], v[32:35]
	v_mfma_f32_16x16x32_bf16 v[20:23], v[202:205], v[178:181], v[20:23]
	s_cbranch_scc0 .LBB0_1006
	v_add_u32_e32 v138, s36, v80
	v_add_u32_e32 v126, v138, v81
	s_waitcnt vmcnt(0)
	s_barrier
	ds_read_b128 v[74:77], v126 offset:16384
	v_add3_u32 v102, s36, v81, v82
	ds_read_b128 v[94:97], v102
	ds_read_b128 v[98:101], v126 offset:18432
	ds_read_b128 v[102:105], v102 offset:2048
	ds_read_b128 v[106:109], v126 offset:20480
	ds_read_b128 v[110:113], v126 offset:22528
	ds_read_b128 v[114:117], v126 offset:24576
	ds_read_b128 v[118:121], v126 offset:26624
	v_add3_u32 v134, s36, v83, v82
	v_add_u32_e32 v142, v138, v83
	ds_read_b128 v[122:125], v126 offset:28672
	ds_read_b128 v[126:129], v126 offset:30720
	ds_read_b128 v[130:133], v134
	ds_read_b128 v[134:137], v134 offset:2048
	ds_read_b128 v[138:141], v142 offset:16384
	ds_read_b128 v[146:149], v142 offset:18432
	s_waitcnt lgkmcnt(11)
	v_mfma_f32_16x16x32_bf16 v[56:59], v[98:101], v[94:97], v[56:59]
	s_lshl_b32 s36, s34, 7
	s_lshl_b32 s26, s33, 7
	s_ashr_i32 s27, s26, 31
	v_mfma_f32_16x16x32_bf16 v[60:63], v[74:77], v[94:97], v[60:63]
	s_lshl_b64 s[26:27], s[26:27], 1
	s_add_i32 s31, s31, s28
	s_cmpk_gt_i32 s31, 0x107f
	s_waitcnt lgkmcnt(0)
	v_mfma_f32_16x16x32_bf16 v[56:59], v[146:149], v[130:133], v[56:59]
	v_mfma_f32_16x16x32_bf16 v[48:51], v[110:113], v[94:97], v[48:51]
	v_mfma_f32_16x16x32_bf16 v[52:55], v[106:109], v[94:97], v[52:55]
	s_nop 5
	v_max_f32_e32 v56, v56, v56
	v_max_f32_e32 v57, v57, v57
	v_max_f32_e32 v56, 0, v56
	v_mfma_f32_16x16x32_bf16 v[44:47], v[114:117], v[94:97], v[44:47]
	v_max_f32_e32 v57, 0, v57
	v_max_f32_e32 v59, v59, v59
	v_max_f32_e32 v59, 0, v59
	v_mfma_f32_16x16x32_bf16 v[40:43], v[118:121], v[94:97], v[40:43]
	v_mfma_f32_16x16x32_bf16 v[36:39], v[122:125], v[94:97], v[36:39]
	v_mfma_f32_16x16x32_bf16 v[32:35], v[126:129], v[94:97], v[32:35]
	ds_read_b128 v[94:97], v142 offset:20480
	ds_read_b128 v[150:153], v142 offset:22528
	ds_read_b128 v[154:157], v142 offset:24576
	ds_read_b128 v[158:161], v142 offset:26624
	v_mfma_f32_16x16x32_bf16 v[60:63], v[138:141], v[130:133], v[60:63]
	s_waitcnt lgkmcnt(2)
	v_mfma_f32_16x16x32_bf16 v[48:51], v[150:153], v[130:133], v[48:51]
	v_mfma_f32_16x16x32_bf16 v[16:19], v[106:109], v[102:105], v[16:19]
	v_mul_f32_e64 v106, v56, v56
	v_mul_f32_e64 v107, v57, v57
	v_max_f32_e32 v57, v58, v58
	s_nop 1
	v_max_f32_e32 v60, v60, v60
	v_mfma_f32_16x16x32_bf16 v[24:27], v[98:101], v[102:105], v[24:27]
	v_add_u32_e32 v100, s36, v79
	v_mov_b64_e32 v[98:99], s[0:1]
	v_max_f32_e32 v61, v61, v61
	v_max_f32_e32 v56, v62, v62
	v_max_f32_e32 v58, 0, v57
	v_max_f32_e32 v57, v63, v63
	v_mad_i64_i32 v[100:101], s[34:35], v100, s30, v[98:99]
	v_max_f32_e32 v60, 0, v60
	v_max_f32_e32 v61, 0, v61
	v_max_f32_e32 v56, 0, v56
	v_max_f32_e32 v57, 0, v57
	v_mfma_f32_16x16x32_bf16 v[52:55], v[94:97], v[130:133], v[52:55]
	v_lshl_add_u64 v[100:101], v[100:101], 0, s[26:27]
	v_pk_mul_f32 v[60:61], v[60:61], v[60:61]
	v_pk_mul_f32 v[62:63], v[56:57], v[56:57]
	v_mfma_f32_16x16x32_bf16 v[28:31], v[74:77], v[102:105], v[28:31]
	v_max_f32_e32 v48, v48, v48
	v_max_f32_e32 v49, v49, v49
	ds_read_b128 v[74:77], v142 offset:28672
	ds_read_b128 v[162:165], v142 offset:30720
	v_mfma_f32_16x16x32_bf16 v[12:15], v[110:113], v[102:105], v[12:15]
	v_lshl_add_u64 v[100:101], v[100:101], 0, v[64:65]
	v_cvt_pk_bf16_f32 v56, v60, v61
	v_cvt_pk_bf16_f32 v57, v62, v63
	v_mfma_f32_16x16x32_bf16 v[8:11], v[114:117], v[102:105], v[8:11]
	v_max_f32_e32 v48, 0, v48
	v_max_f32_e32 v49, 0, v49
	v_max_f32_e32 v52, v52, v52
	v_mfma_f32_16x16x32_bf16 v[4:7], v[118:121], v[102:105], v[4:7]
	v_max_f32_e32 v53, v53, v53
	v_max_f32_e32 v51, v51, v51
	v_max_f32_e32 v52, 0, v52
	v_mfma_f32_16x16x32_bf16 v[0:3], v[122:125], v[102:105], v[0:3]
	v_max_f32_e32 v53, 0, v53
	v_max_f32_e32 v51, 0, v51
	v_pk_mul_f32 v[52:53], v[52:53], v[52:53]
	v_mfma_f32_16x16x32_bf16 v[20:23], v[126:129], v[102:105], v[20:23]
	v_mul_f32_e64 v102, v58, v58
	v_mul_f32_e64 v103, v59, v59
	v_cvt_pk_bf16_f32 v58, v106, v107
	v_cvt_pk_bf16_f32 v59, v102, v103
	s_waitcnt lgkmcnt(2)
	v_mfma_f32_16x16x32_bf16 v[40:43], v[158:161], v[130:133], v[40:43]
	global_store_dwordx4 v[100:101], v[56:59], off
	s_nop 1
	v_pk_mul_f32 v[56:57], v[48:49], v[48:49]
	v_max_f32_e32 v49, v50, v50
	v_max_f32_e32 v48, v54, v54
	v_max_f32_e32 v50, 0, v49
	v_max_f32_e32 v49, v55, v55
	v_mfma_f32_16x16x32_bf16 v[44:47], v[154:157], v[130:133], v[44:47]
	v_max_f32_e32 v48, 0, v48
	v_max_f32_e32 v49, 0, v49
	v_pk_mul_f32 v[54:55], v[48:49], v[48:49]
	v_pk_mul_f32 v[58:59], v[50:51], v[50:51]
	v_max_f32_e32 v40, v40, v40
	v_max_f32_e32 v41, v41, v41
	s_waitcnt lgkmcnt(0)
	v_mfma_f32_16x16x32_bf16 v[32:35], v[162:165], v[130:133], v[32:35]
	v_cvt_pk_bf16_f32 v48, v52, v53
	v_cvt_pk_bf16_f32 v49, v54, v55
	v_cvt_pk_bf16_f32 v50, v56, v57
	v_cvt_pk_bf16_f32 v51, v58, v59
	v_max_f32_e32 v40, 0, v40
	v_max_f32_e32 v41, 0, v41
	global_store_dwordx4 v[100:101], v[48:51], off offset:64
	v_max_f32_e32 v44, v44, v44
	v_max_f32_e32 v45, v45, v45
	v_pk_mul_f32 v[48:49], v[40:41], v[40:41]
	v_max_f32_e32 v41, v42, v42
	v_max_f32_e32 v40, v46, v46
	v_max_f32_e32 v42, 0, v41
	v_max_f32_e32 v41, v47, v47
	v_max_f32_e32 v43, v43, v43
	v_mfma_f32_16x16x32_bf16 v[36:39], v[74:77], v[130:133], v[36:39]
	v_max_f32_e32 v44, 0, v44
	v_max_f32_e32 v45, 0, v45
	v_max_f32_e32 v40, 0, v40
	v_max_f32_e32 v41, 0, v41
	v_max_f32_e32 v43, 0, v43
	v_pk_mul_f32 v[44:45], v[44:45], v[44:45]
	v_pk_mul_f32 v[46:47], v[40:41], v[40:41]
	v_pk_mul_f32 v[50:51], v[42:43], v[42:43]
	v_max_f32_e32 v32, v32, v32
	v_max_f32_e32 v33, v33, v33
	v_mfma_f32_16x16x32_bf16 v[24:27], v[146:149], v[134:137], v[24:27]
	v_cvt_pk_bf16_f32 v40, v44, v45
	v_cvt_pk_bf16_f32 v41, v46, v47
	v_cvt_pk_bf16_f32 v42, v48, v49
	v_cvt_pk_bf16_f32 v43, v50, v51
	v_max_f32_e32 v32, 0, v32
	v_max_f32_e32 v33, 0, v33
	global_store_dwordx4 v[100:101], v[40:43], off offset:128
	v_max_f32_e32 v36, v36, v36
	v_max_f32_e32 v37, v37, v37
	v_pk_mul_f32 v[40:41], v[32:33], v[32:33]
	v_max_f32_e32 v33, v34, v34
	v_max_f32_e32 v32, v38, v38
	v_max_f32_e32 v34, 0, v33
	v_max_f32_e32 v33, v39, v39
	v_max_f32_e32 v35, v35, v35
	v_mfma_f32_16x16x32_bf16 v[28:31], v[138:141], v[134:137], v[28:31]
	v_max_f32_e32 v36, 0, v36
	v_max_f32_e32 v37, 0, v37
	v_max_f32_e32 v32, 0, v32
	v_max_f32_e32 v33, 0, v33
	v_max_f32_e32 v35, 0, v35
	v_pk_mul_f32 v[36:37], v[36:37], v[36:37]
	v_pk_mul_f32 v[38:39], v[32:33], v[32:33]
	v_pk_mul_f32 v[42:43], v[34:35], v[34:35]
	v_max_f32_e32 v24, v24, v24
	v_max_f32_e32 v25, v25, v25
	v_mfma_f32_16x16x32_bf16 v[12:15], v[150:153], v[134:137], v[12:15]
	v_cvt_pk_bf16_f32 v32, v36, v37
	v_cvt_pk_bf16_f32 v33, v38, v39
	v_cvt_pk_bf16_f32 v34, v40, v41
	v_cvt_pk_bf16_f32 v35, v42, v43
	v_max_f32_e32 v24, 0, v24
	v_max_f32_e32 v25, 0, v25
	global_store_dwordx4 v[100:101], v[32:35], off offset:192
	v_max_f32_e32 v28, v28, v28
	v_max_f32_e32 v29, v29, v29
	v_pk_mul_f32 v[34:35], v[24:25], v[24:25]
	v_max_f32_e32 v25, v26, v26
	v_add_u32_e32 v32, s36, v84
	v_max_f32_e32 v24, v30, v30
	v_max_f32_e32 v26, 0, v25
	v_max_f32_e32 v25, v31, v31
	v_max_f32_e32 v27, v27, v27
	v_mfma_f32_16x16x32_bf16 v[16:19], v[94:97], v[134:137], v[16:19]
	v_mad_i64_i32 v[32:33], s[34:35], v32, s30, v[98:99]
	v_max_f32_e32 v28, 0, v28
	v_max_f32_e32 v29, 0, v29
	v_max_f32_e32 v24, 0, v24
	v_max_f32_e32 v25, 0, v25
	v_max_f32_e32 v27, 0, v27
	v_lshl_add_u64 v[32:33], v[32:33], 0, s[26:27]
	v_pk_mul_f32 v[28:29], v[28:29], v[28:29]
	v_pk_mul_f32 v[30:31], v[24:25], v[24:25]
	v_pk_mul_f32 v[36:37], v[26:27], v[26:27]
	v_max_f32_e32 v12, v12, v12
	v_max_f32_e32 v13, v13, v13
	v_mfma_f32_16x16x32_bf16 v[4:7], v[158:161], v[134:137], v[4:7]
	v_lshl_add_u64 v[32:33], v[32:33], 0, v[64:65]
	v_cvt_pk_bf16_f32 v24, v28, v29
	v_cvt_pk_bf16_f32 v25, v30, v31
	v_cvt_pk_bf16_f32 v26, v34, v35
	v_cvt_pk_bf16_f32 v27, v36, v37
	v_max_f32_e32 v12, 0, v12
	v_max_f32_e32 v13, 0, v13
	global_store_dwordx4 v[32:33], v[24:27], off
	v_max_f32_e32 v16, v16, v16
	v_max_f32_e32 v17, v17, v17
	v_pk_mul_f32 v[24:25], v[12:13], v[12:13]
	v_max_f32_e32 v13, v14, v14
	v_max_f32_e32 v12, v18, v18
	v_max_f32_e32 v14, 0, v13
	v_max_f32_e32 v13, v19, v19
	v_max_f32_e32 v15, v15, v15
	v_mfma_f32_16x16x32_bf16 v[8:11], v[154:157], v[134:137], v[8:11]
	v_max_f32_e32 v16, 0, v16
	v_max_f32_e32 v17, 0, v17
	v_max_f32_e32 v12, 0, v12
	v_max_f32_e32 v13, 0, v13
	v_max_f32_e32 v15, 0, v15
	v_pk_mul_f32 v[16:17], v[16:17], v[16:17]
	v_pk_mul_f32 v[18:19], v[12:13], v[12:13]
	v_pk_mul_f32 v[26:27], v[14:15], v[14:15]
	v_max_f32_e32 v4, v4, v4
	v_max_f32_e32 v5, v5, v5
	v_cvt_pk_bf16_f32 v12, v16, v17
	v_cvt_pk_bf16_f32 v13, v18, v19
	v_cvt_pk_bf16_f32 v14, v24, v25
	v_cvt_pk_bf16_f32 v15, v26, v27
	v_max_f32_e32 v4, 0, v4
	v_max_f32_e32 v5, 0, v5
	global_store_dwordx4 v[32:33], v[12:15], off offset:64
	v_mfma_f32_16x16x32_bf16 v[0:3], v[74:77], v[134:137], v[0:3]
	v_max_f32_e32 v8, v8, v8
	v_pk_mul_f32 v[12:13], v[4:5], v[4:5]
	v_max_f32_e32 v5, v6, v6
	v_mfma_f32_16x16x32_bf16 v[20:23], v[162:165], v[134:137], v[20:23]
	v_max_f32_e32 v9, v9, v9
	v_max_f32_e32 v4, v10, v10
	v_max_f32_e32 v6, 0, v5
	v_max_f32_e32 v5, v11, v11
	v_max_f32_e32 v7, v7, v7
	v_max_f32_e32 v8, 0, v8
	v_max_f32_e32 v9, 0, v9
	v_max_f32_e32 v4, 0, v4
	v_max_f32_e32 v5, 0, v5
	v_max_f32_e32 v7, 0, v7
	v_pk_mul_f32 v[8:9], v[8:9], v[8:9]
	v_pk_mul_f32 v[10:11], v[4:5], v[4:5]
	v_pk_mul_f32 v[14:15], v[6:7], v[6:7]
	v_cvt_pk_bf16_f32 v4, v8, v9
	v_cvt_pk_bf16_f32 v5, v10, v11
	v_cvt_pk_bf16_f32 v6, v12, v13
	v_cvt_pk_bf16_f32 v7, v14, v15
	global_store_dwordx4 v[32:33], v[4:7], off offset:128
	v_max_f32_e32 v0, v0, v0
	v_max_f32_e32 v1, v1, v1
	v_max_f32_e32 v4, v20, v20
	v_max_f32_e32 v5, v21, v21
	v_max_f32_e32 v2, v2, v2
	v_max_f32_e32 v6, v22, v22
	v_max_f32_e32 v3, v3, v3
	v_max_f32_e32 v7, v23, v23
	v_max_f32_e32 v0, 0, v0
	v_max_f32_e32 v4, 0, v4
	v_max_f32_e32 v1, 0, v1
	v_max_f32_e32 v5, 0, v5
	v_max_f32_e32 v2, 0, v2
	v_max_f32_e32 v6, 0, v6
	v_max_f32_e32 v3, 0, v3
	v_max_f32_e32 v7, 0, v7
	v_pk_mul_f32 v[0:1], v[0:1], v[0:1]
	v_pk_mul_f32 v[4:5], v[4:5], v[4:5]
	v_pk_mul_f32 v[2:3], v[2:3], v[2:3]
	v_pk_mul_f32 v[6:7], v[6:7], v[6:7]
	v_cvt_pk_bf16_f32 v0, v0, v1
	v_cvt_pk_bf16_f32 v1, v2, v3
	v_cvt_pk_bf16_f32 v2, v4, v5
	v_cvt_pk_bf16_f32 v3, v6, v7
	global_store_dwordx4 v[32:33], v[0:3], off offset:192
	s_cbranch_scc0 .LBB0_1005

.LBB0_1071:
	s_add_i32 s45, s43, 0x8000
	s_and_b32 s44, s45, 0x8000
	s_add_i32 s44, s44, 0
	s_and_b32 s43, s43, 0x8000
	s_add_i32 s43, s43, 0
	s_add_u32 s86, s43, s87
	s_waitcnt vmcnt(8)
	s_barrier
	v_add3_u32 v169, s43, v84, v89
	v_add3_u32 v210, s43, v89, v90
	v_add3_u32 v211, s43, v84, v91
	v_add3_u32 v212, s43, v90, v91
	ds_read_b128 v[106:109], v210
	ds_read_b128 v[76:79], v169 offset:16384
	ds_read_b128 v[102:105], v169 offset:18432
	ds_read_b128 v[110:113], v210 offset:2048
	ds_read_b128 v[114:117], v169 offset:20480
	ds_read_b128 v[118:121], v169 offset:22528
	ds_read_b128 v[122:125], v169 offset:24576
	ds_read_b128 v[126:129], v169 offset:26624
	ds_read_b128 v[130:133], v169 offset:28672
	ds_read_b128 v[134:137], v169 offset:30720
	ds_read_b128 v[178:181], v212
	ds_read_b128 v[170:173], v211 offset:16384
	ds_read_b128 v[174:177], v211 offset:18432
	ds_read_b128 v[182:185], v212 offset:2048
	ds_read_b128 v[186:189], v211 offset:20480
	ds_read_b128 v[190:193], v211 offset:22528
	ds_read_b128 v[194:197], v211 offset:24576
	ds_read_b128 v[198:201], v211 offset:26624
	ds_read_b128 v[202:205], v211 offset:28672
	ds_read_b128 v[206:209], v211 offset:30720
	s_waitcnt lgkmcnt(15)
	v_mfma_f32_16x16x32_bf16 v[60:63], v[76:79], v[106:109], v[60:63]
	v_mfma_f32_16x16x32_bf16 v[56:59], v[102:105], v[106:109], v[56:59]
	v_mfma_f32_16x16x32_bf16 v[24:27], v[76:79], v[110:113], v[24:27]
	v_mfma_f32_16x16x32_bf16 v[20:23], v[102:105], v[110:113], v[20:23]
	v_mfma_f32_16x16x32_bf16 v[52:55], v[114:117], v[106:109], v[52:55]
	v_mfma_f32_16x16x32_bf16 v[16:19], v[114:117], v[110:113], v[16:19]
	s_waitcnt lgkmcnt(14)
	v_mfma_f32_16x16x32_bf16 v[48:51], v[118:121], v[106:109], v[48:51]
	v_mfma_f32_16x16x32_bf16 v[12:15], v[118:121], v[110:113], v[12:15]
	s_waitcnt lgkmcnt(13)
	v_mfma_f32_16x16x32_bf16 v[44:47], v[122:125], v[106:109], v[44:47]
	v_mfma_f32_16x16x32_bf16 v[8:11], v[122:125], v[110:113], v[8:11]
	s_waitcnt lgkmcnt(12)
	v_mfma_f32_16x16x32_bf16 v[40:43], v[126:129], v[106:109], v[40:43]
	v_mfma_f32_16x16x32_bf16 v[4:7], v[126:129], v[110:113], v[4:7]
	s_waitcnt lgkmcnt(11)
	v_mfma_f32_16x16x32_bf16 v[32:35], v[130:133], v[106:109], v[32:35]
	v_mfma_f32_16x16x32_bf16 v[0:3], v[130:133], v[110:113], v[0:3]
	s_waitcnt lgkmcnt(10)
	v_mfma_f32_16x16x32_bf16 v[28:31], v[134:137], v[106:109], v[28:31]
	v_mfma_f32_16x16x32_bf16 v[36:39], v[134:137], v[110:113], v[36:39]
	s_waitcnt lgkmcnt(0)
	s_barrier
	s_cmpk_eq_i32 s34, 0x1f00
	s_cbranch_scc1 .Lgskip_1071
	s_mov_b32 m0, s86
	s_nop 0
	global_load_lds_dwordx4 v244, s[96:97]
	s_add_u32 m0, s86, 0x4000
	s_nop 0
	global_load_lds_dwordx4 v245, s[88:89]
	s_add_u32 m0, s86, 0x1000
	s_nop 0
	global_load_lds_dwordx4 v246, s[96:97]
	s_add_u32 m0, s86, 0x5000
	s_nop 0
	global_load_lds_dwordx4 v247, s[88:89]
	s_add_u32 m0, s86, 0x2000
	s_nop 0
	global_load_lds_dwordx4 v248, s[96:97]
	s_add_u32 m0, s86, 0x6000
	s_nop 0
	global_load_lds_dwordx4 v249, s[88:89]
	s_add_u32 m0, s86, 0x3000
	s_nop 0
	global_load_lds_dwordx4 v250, s[96:97]
	s_add_u32 m0, s86, 0x7000
	s_nop 0
	global_load_lds_dwordx4 v251, s[88:89]
	s_add_u32 s96, s96, 0x80
	s_addc_u32 s97, s97, 0
	s_add_u32 s88, s88, 0x80
	s_addc_u32 s89, s89, 0
.Lgskip_1071:
	s_add_u32 s34, s34, 0x80
	s_addc_u32 s35, s35, 0
	s_cmpk_eq_i32 s34, 0x1f80
	s_mov_b32 s43, s45
	v_mfma_f32_16x16x32_bf16 v[60:63], v[170:173], v[178:181], v[60:63]
	v_mfma_f32_16x16x32_bf16 v[56:59], v[174:177], v[178:181], v[56:59]
	v_mfma_f32_16x16x32_bf16 v[24:27], v[170:173], v[182:185], v[24:27]
	v_mfma_f32_16x16x32_bf16 v[20:23], v[174:177], v[182:185], v[20:23]
	v_mfma_f32_16x16x32_bf16 v[52:55], v[186:189], v[178:181], v[52:55]
	v_mfma_f32_16x16x32_bf16 v[16:19], v[186:189], v[182:185], v[16:19]
	v_mfma_f32_16x16x32_bf16 v[48:51], v[190:193], v[178:181], v[48:51]
	v_mfma_f32_16x16x32_bf16 v[12:15], v[190:193], v[182:185], v[12:15]
	v_mfma_f32_16x16x32_bf16 v[44:47], v[194:197], v[178:181], v[44:47]
	v_mfma_f32_16x16x32_bf16 v[8:11], v[194:197], v[182:185], v[8:11]
	v_mfma_f32_16x16x32_bf16 v[40:43], v[198:201], v[178:181], v[40:43]
	v_mfma_f32_16x16x32_bf16 v[4:7], v[198:201], v[182:185], v[4:7]
	v_mfma_f32_16x16x32_bf16 v[32:35], v[202:205], v[178:181], v[32:35]
	v_mfma_f32_16x16x32_bf16 v[0:3], v[202:205], v[182:185], v[0:3]
	v_mfma_f32_16x16x32_bf16 v[28:31], v[206:209], v[178:181], v[28:31]
	v_mfma_f32_16x16x32_bf16 v[36:39], v[206:209], v[182:185], v[36:39]
	s_cbranch_scc0 .LBB0_1071
	v_add_u32_e32 v80, s44, v84
	v_add_u32_e32 v81, v80, v89
	v_add3_u32 v106, s44, v89, v90
	s_waitcnt vmcnt(0)
	s_barrier
	ds_read_b128 v[72:75], v81 offset:16384
	ds_read_b128 v[76:79], v81 offset:18432
	ds_read_b128 v[102:105], v106
	ds_read_b128 v[106:109], v106 offset:2048
	ds_read_b128 v[110:113], v81 offset:20480
	ds_read_b128 v[114:117], v81 offset:22528
	ds_read_b128 v[118:121], v81 offset:24576
	ds_read_b128 v[122:125], v81 offset:26624
	ds_read_b128 v[126:129], v81 offset:28672
	ds_read_b128 v[130:133], v81 offset:30720
	v_add_u32_e32 v80, v80, v91
	s_waitcnt lgkmcnt(7)
	v_mfma_f32_16x16x32_bf16 v[60:63], v[72:75], v[102:105], v[60:63]
	s_lshl_b32 s42, s42, 7
	v_mfma_f32_16x16x32_bf16 v[56:59], v[76:79], v[102:105], v[56:59]
	s_waitcnt lgkmcnt(4)
	v_mfma_f32_16x16x32_bf16 v[48:51], v[114:117], v[102:105], v[48:51]
	s_waitcnt lgkmcnt(3)
	v_mfma_f32_16x16x32_bf16 v[44:47], v[118:121], v[102:105], v[44:47]
	s_waitcnt lgkmcnt(2)
	v_mfma_f32_16x16x32_bf16 v[40:43], v[122:125], v[102:105], v[40:43]
	s_waitcnt lgkmcnt(1)
	v_mfma_f32_16x16x32_bf16 v[32:35], v[126:129], v[102:105], v[32:35]
	s_waitcnt lgkmcnt(0)
	v_mfma_f32_16x16x32_bf16 v[28:31], v[130:133], v[102:105], v[28:31]
	v_mfma_f32_16x16x32_bf16 v[24:27], v[72:75], v[106:109], v[24:27]
	ds_read_b128 v[72:75], v80 offset:16384
	v_mfma_f32_16x16x32_bf16 v[52:55], v[110:113], v[102:105], v[52:55]
	v_mfma_f32_16x16x32_bf16 v[20:23], v[76:79], v[106:109], v[20:23]
	v_mfma_f32_16x16x32_bf16 v[16:19], v[110:113], v[106:109], v[16:19]
	v_mfma_f32_16x16x32_bf16 v[12:15], v[114:117], v[106:109], v[12:15]
	v_mfma_f32_16x16x32_bf16 v[8:11], v[118:121], v[106:109], v[8:11]
	v_mfma_f32_16x16x32_bf16 v[4:7], v[122:125], v[106:109], v[4:7]
	v_mfma_f32_16x16x32_bf16 v[0:3], v[126:129], v[106:109], v[0:3]
	v_mfma_f32_16x16x32_bf16 v[102:105], v[130:133], v[106:109], v[36:39]
	s_nop 2
	v_add3_u32 v36, s44, v91, v90
	ds_read_b128 v[76:79], v80 offset:18432
	ds_read_b128 v[106:109], v36
	ds_read_b128 v[110:113], v36 offset:2048
	ds_read_b128 v[130:133], v80 offset:28672
	ds_read_b128 v[134:137], v80 offset:30720
	ds_read_b128 v[114:117], v80 offset:20480
	ds_read_b128 v[118:121], v80 offset:22528
	ds_read_b128 v[122:125], v80 offset:24576
	ds_read_b128 v[126:129], v80 offset:26624
	s_waitcnt lgkmcnt(7)
	v_mfma_f32_16x16x32_bf16 v[60:63], v[72:75], v[106:109], v[60:63]
	s_waitcnt lgkmcnt(5)
	v_mfma_f32_16x16x32_bf16 v[36:39], v[130:133], v[106:109], v[32:35]
	s_waitcnt lgkmcnt(4)
	v_mfma_f32_16x16x32_bf16 v[32:35], v[134:137], v[106:109], v[28:31]
	v_mfma_f32_16x16x32_bf16 v[28:31], v[72:75], v[110:113], v[24:27]
	v_add_u32_e32 v72, s42, v85
	v_mul_hi_i32 v73, v72, s36
	v_mfma_f32_16x16x32_bf16 v[24:27], v[76:79], v[110:113], v[20:23]
	s_waitcnt lgkmcnt(3)
	v_mfma_f32_16x16x32_bf16 v[20:23], v[114:117], v[110:113], v[16:19]
	s_waitcnt lgkmcnt(2)
	v_mfma_f32_16x16x32_bf16 v[16:19], v[118:121], v[110:113], v[12:15]
	s_waitcnt lgkmcnt(1)
	v_mfma_f32_16x16x32_bf16 v[12:15], v[122:125], v[110:113], v[8:11]
	s_waitcnt lgkmcnt(0)
	v_mfma_f32_16x16x32_bf16 v[8:11], v[126:129], v[110:113], v[4:7]
	s_nop 2
	v_lshrrev_b32_e32 v4, 31, v73
	v_ashrrev_i32_e32 v5, 11, v73
	v_mfma_f32_16x16x32_bf16 v[56:59], v[76:79], v[106:109], v[56:59]
	v_add_u32_e32 v73, v5, v4
	v_mad_i32_i24 v78, v73, s37, v72
	v_lshlrev_b32_e32 v75, 13, v73
	v_mfma_f32_16x16x32_bf16 v[52:55], v[114:117], v[106:109], v[52:55]
	v_cmp_lt_i32_e32 vcc, s38, v78
	v_add3_u32 v74, v75, v78, s39
	v_mfma_f32_16x16x32_bf16 v[48:51], v[118:121], v[106:109], v[48:51]
	v_mfma_f32_16x16x32_bf16 v[44:47], v[122:125], v[106:109], v[44:47]
	v_mfma_f32_16x16x32_bf16 v[40:43], v[126:129], v[106:109], v[40:43]
	v_mfma_f32_16x16x32_bf16 v[4:7], v[130:133], v[110:113], v[0:3]
	v_mfma_f32_16x16x32_bf16 v[0:3], v[134:137], v[110:113], v[102:105]
	s_and_saveexec_b64 s[34:35], vcc
	s_xor_b64 s[34:35], exec, s[34:35]
	v_add3_u32 v72, v75, v78, s39
	s_or_saveexec_b64 s[34:35], s[34:35]
	v_mov_b64_e32 v[76:77], s[92:93]
	v_lshl_add_u32 v75, v73, 8, v78
	s_xor_b64 exec, exec, s[34:35]
	v_lshl_add_u32 v72, v73, 8, v78
	v_mov_b64_e32 v[76:77], s[6:7]
	s_or_b64 exec, exec, s[34:35]
	s_and_saveexec_b64 s[34:35], vcc
	s_xor_b64 s[34:35], exec, s[34:35]
	s_cbranch_execz .LBB0_1078
	v_mul_hi_i32_i24_e32 v79, 0x6000, v73
	v_mul_i32_i24_e32 v78, 0x6000, v73
	s_or_saveexec_b64 s[34:35], s[34:35]
	v_mov_b64_e32 v[80:81], s[92:93]
	s_xor_b64 exec, exec, s[34:35]
	s_cbranch_execnz .LBB0_1079
	s_branch .LBB0_1080

.LBB0_1091:
	s_add_i32 s48, s47, 0x8000
	s_and_b32 s8, s47, 0x8000
	s_and_b32 s47, s48, 0x8000
	s_add_i32 s49, s8, 0
	s_add_i32 s8, s47, 0
	s_add_u32 s71, s49, s75
	s_waitcnt vmcnt(8)
	s_barrier
	v_add3_u32 v169, s49, v84, v87
	v_add3_u32 v210, s49, v87, v89
	v_add3_u32 v211, s49, v84, v90
	v_add3_u32 v212, s49, v89, v90
	ds_read_b128 v[104:107], v210
	ds_read_b128 v[68:71], v169 offset:16384
	ds_read_b128 v[100:103], v169 offset:18432
	ds_read_b128 v[108:111], v210 offset:2048
	ds_read_b128 v[112:115], v169 offset:20480
	ds_read_b128 v[116:119], v169 offset:22528
	ds_read_b128 v[120:123], v169 offset:24576
	ds_read_b128 v[124:127], v169 offset:26624
	ds_read_b128 v[128:131], v169 offset:28672
	ds_read_b128 v[132:135], v169 offset:30720
	ds_read_b128 v[178:181], v212
	ds_read_b128 v[170:173], v211 offset:16384
	ds_read_b128 v[174:177], v211 offset:18432
	ds_read_b128 v[182:185], v212 offset:2048
	ds_read_b128 v[186:189], v211 offset:20480
	ds_read_b128 v[190:193], v211 offset:22528
	ds_read_b128 v[194:197], v211 offset:24576
	ds_read_b128 v[198:201], v211 offset:26624
	ds_read_b128 v[202:205], v211 offset:28672
	ds_read_b128 v[206:209], v211 offset:30720
	s_waitcnt lgkmcnt(15)
	v_mfma_f32_16x16x32_bf16 v[60:63], v[68:71], v[104:107], v[60:63]
	v_mfma_f32_16x16x32_bf16 v[56:59], v[100:103], v[104:107], v[56:59]
	v_mfma_f32_16x16x32_bf16 v[28:31], v[68:71], v[108:111], v[28:31]
	v_mfma_f32_16x16x32_bf16 v[24:27], v[100:103], v[108:111], v[24:27]
	v_mfma_f32_16x16x32_bf16 v[52:55], v[112:115], v[104:107], v[52:55]
	v_mfma_f32_16x16x32_bf16 v[16:19], v[112:115], v[108:111], v[16:19]
	s_waitcnt lgkmcnt(14)
	v_mfma_f32_16x16x32_bf16 v[48:51], v[116:119], v[104:107], v[48:51]
	v_mfma_f32_16x16x32_bf16 v[12:15], v[116:119], v[108:111], v[12:15]
	s_waitcnt lgkmcnt(13)
	v_mfma_f32_16x16x32_bf16 v[44:47], v[120:123], v[104:107], v[44:47]
	v_mfma_f32_16x16x32_bf16 v[8:11], v[120:123], v[108:111], v[8:11]
	s_waitcnt lgkmcnt(12)
	v_mfma_f32_16x16x32_bf16 v[40:43], v[124:127], v[104:107], v[40:43]
	v_mfma_f32_16x16x32_bf16 v[4:7], v[124:127], v[108:111], v[4:7]
	s_waitcnt lgkmcnt(11)
	v_mfma_f32_16x16x32_bf16 v[36:39], v[128:131], v[104:107], v[36:39]
	v_mfma_f32_16x16x32_bf16 v[0:3], v[128:131], v[108:111], v[0:3]
	s_waitcnt lgkmcnt(10)
	v_mfma_f32_16x16x32_bf16 v[32:35], v[132:135], v[104:107], v[32:35]
	v_mfma_f32_16x16x32_bf16 v[20:23], v[132:135], v[108:111], v[20:23]
	s_waitcnt lgkmcnt(0)
	s_barrier
	s_cmpk_eq_i32 s36, 0x700
	s_cbranch_scc1 .Lgskip_1091
	s_mov_b32 m0, s71
	s_nop 0
	global_load_lds_dwordx4 v236, s[84:85]
	s_add_u32 m0, s71, 0x4000
	s_nop 0
	global_load_lds_dwordx4 v237, s[72:73]
	s_add_u32 m0, s71, 0x1000
	s_nop 0
	global_load_lds_dwordx4 v238, s[84:85]
	s_add_u32 m0, s71, 0x5000
	s_nop 0
	global_load_lds_dwordx4 v239, s[72:73]
	s_add_u32 m0, s71, 0x2000
	s_nop 0
	global_load_lds_dwordx4 v240, s[84:85]
	s_add_u32 m0, s71, 0x6000
	s_nop 0
	global_load_lds_dwordx4 v241, s[72:73]
	s_add_u32 m0, s71, 0x3000
	s_nop 0
	global_load_lds_dwordx4 v242, s[84:85]
	s_add_u32 m0, s71, 0x7000
	s_nop 0
	global_load_lds_dwordx4 v243, s[72:73]
	s_add_u32 s84, s84, 0x80
	s_addc_u32 s85, s85, 0
	s_add_u32 s72, s72, 0x80
	s_addc_u32 s73, s73, 0
.Lgskip_1091:
	s_add_u32 s36, s36, 0x80
	s_addc_u32 s37, s37, 0
	s_cmpk_eq_i32 s36, 0x780
	s_mov_b32 s47, s48
	v_mfma_f32_16x16x32_bf16 v[60:63], v[170:173], v[178:181], v[60:63]
	v_mfma_f32_16x16x32_bf16 v[56:59], v[174:177], v[178:181], v[56:59]
	v_mfma_f32_16x16x32_bf16 v[28:31], v[170:173], v[182:185], v[28:31]
	v_mfma_f32_16x16x32_bf16 v[24:27], v[174:177], v[182:185], v[24:27]
	v_mfma_f32_16x16x32_bf16 v[52:55], v[186:189], v[178:181], v[52:55]
	v_mfma_f32_16x16x32_bf16 v[16:19], v[186:189], v[182:185], v[16:19]
	v_mfma_f32_16x16x32_bf16 v[48:51], v[190:193], v[178:181], v[48:51]
	v_mfma_f32_16x16x32_bf16 v[12:15], v[190:193], v[182:185], v[12:15]
	v_mfma_f32_16x16x32_bf16 v[44:47], v[194:197], v[178:181], v[44:47]
	v_mfma_f32_16x16x32_bf16 v[8:11], v[194:197], v[182:185], v[8:11]
	v_mfma_f32_16x16x32_bf16 v[40:43], v[198:201], v[178:181], v[40:43]
	v_mfma_f32_16x16x32_bf16 v[4:7], v[198:201], v[182:185], v[4:7]
	v_mfma_f32_16x16x32_bf16 v[36:39], v[202:205], v[178:181], v[36:39]
	v_mfma_f32_16x16x32_bf16 v[0:3], v[202:205], v[182:185], v[0:3]
	v_mfma_f32_16x16x32_bf16 v[32:35], v[206:209], v[178:181], v[32:35]
	v_mfma_f32_16x16x32_bf16 v[20:23], v[206:209], v[182:185], v[20:23]
	s_cbranch_scc0 .LBB0_1091
	v_lshl_add_u32 v99, s46, 7, v85
	v_mul_hi_i32 v64, v99, s39
	v_lshrrev_b32_e32 v65, 31, v64
	v_ashrrev_i32_e32 v64, 11, v64
	v_add_u32_e32 v64, v64, v65
	v_mad_i32_i24 v65, v64, s40, v99
	v_cmp_lt_i32_e32 vcc, s41, v65
	v_lshl_or_b32 v72, s45, 9, v86
	s_waitcnt vmcnt(0)
	v_cndmask_b32_e32 v64, 2, v64, vcc
	v_mul_hi_i32_i24_e32 v65, 0x6000, v64
	v_mul_i32_i24_e32 v64, 0x6000, v64
	v_lshl_add_u64 v[64:65], s[94:95], 0, v[64:65]
	v_lshl_add_u64 v[150:151], v[64:65], 0, s[34:35]
	v_lshl_add_u64 v[64:65], v[150:151], 0, v[72:73]
	s_barrier
	global_load_dwordx4 v[100:103], v[64:65], off
	v_add3_u32 v64, s8, v87, v89
	v_add_u32_e32 v68, s8, v84
	ds_read_b128 v[104:107], v64
	ds_read_b128 v[108:111], v64 offset:2048
	v_add3_u32 v65, s8, v90, v89
	v_add_u32_e32 v145, v68, v87
	ds_read_b128 v[112:115], v65
	ds_read_b128 v[64:67], v65 offset:2048
	v_add_u32_e32 v168, v68, v90
	ds_read_b128 v[116:119], v145 offset:16384
	ds_read_b128 v[120:123], v145 offset:18432
	ds_read_b128 v[124:127], v168 offset:16384
	ds_read_b128 v[68:71], v168 offset:18432
	v_mul_hi_i32 v128, v99, s38
	s_waitcnt lgkmcnt(3)
	v_mfma_f32_16x16x32_bf16 v[60:63], v[116:119], v[104:107], v[60:63]
	v_lshrrev_b32_e32 v129, 31, v128
	v_lshrrev_b32_e32 v128, 11, v128
	v_add_u32_e32 v128, v128, v129
	v_lshl_add_u32 v128, v128, 13, v99
	s_lshl_b32 s8, s44, 9
	v_ashrrev_i32_e32 v129, 31, v128
	s_waitcnt lgkmcnt(1)
	v_mfma_f32_16x16x32_bf16 v[60:63], v[124:127], v[112:115], v[60:63]
	v_lshl_add_u64 v[128:129], v[128:129], 0, s[8:9]
	v_lshlrev_b64 v[128:129], 12, v[128:129]
	v_lshl_add_u64 v[128:129], s[6:7], 0, v[128:129]
	v_mov_b32_e32 v153, v73
	v_or_b32_e32 v152, 16, v72
	v_lshl_add_u64 v[154:155], v[128:129], 0, v[72:73]
	v_lshl_add_u64 v[128:129], v[150:151], 0, v[152:153]
	v_mfma_f32_16x16x32_bf16 v[56:59], v[120:123], v[104:107], v[56:59]
	v_mov_b32_e32 v157, v73
	v_or_b32_e32 v156, 0x80, v72
	v_mov_b32_e32 v159, v73
	s_waitcnt lgkmcnt(0)
	v_mfma_f32_16x16x32_bf16 v[56:59], v[68:71], v[112:115], v[56:59]
	v_or_b32_e32 v158, 0x90, v72
	v_lshl_add_u64 v[136:137], v[150:151], 0, v[158:159]
	v_mov_b32_e32 v161, v73
	v_or_b32_e32 v160, 0x100, v72
	v_mov_b32_e32 v163, v73
	v_or_b32_e32 v162, 0x110, v72
	v_lshl_add_u64 v[146:147], v[150:151], 0, v[162:163]
	v_mov_b32_e32 v165, v73
	v_or_b32_e32 v164, 0x180, v72
	v_lshl_add_u64 v[166:167], v[150:151], 0, v[164:165]
	v_mfma_f32_16x16x32_bf16 v[28:31], v[116:119], v[108:111], v[28:31]
	v_or_b32_e32 v99, 16, v99
	s_add_i32 s43, s43, s33
	s_add_i32 s42, s42, s33
	v_mfma_f32_16x16x32_bf16 v[28:31], v[124:127], v[64:67], v[28:31]
	s_cmpk_gt_i32 s43, 0x7f
	s_waitcnt vmcnt(0)
	v_pk_mul_f32 v[62:63], v[62:63], v[102:103]
	v_pk_mul_f32 v[60:61], v[60:61], v[100:101]
	global_store_dwordx4 v[154:155], v[60:63], off
	global_load_dwordx4 v[60:63], v[128:129], off
	v_lshl_add_u64 v[100:101], v[150:151], 0, v[156:157]
	v_mfma_f32_16x16x32_bf16 v[24:27], v[120:123], v[108:111], v[24:27]
	s_waitcnt vmcnt(0)
	v_pk_mul_f32 v[58:59], v[58:59], v[62:63]
	v_pk_mul_f32 v[56:57], v[56:57], v[60:61]
	global_store_dwordx4 v[154:155], v[56:59], off offset:16
	global_load_dwordx4 v[56:59], v[100:101], off
	ds_read_b128 v[60:63], v145 offset:20480
	ds_read_b128 v[100:103], v168 offset:20480
	s_waitcnt lgkmcnt(1)
	v_mfma_f32_16x16x32_bf16 v[52:55], v[60:63], v[104:107], v[52:55]
	ds_read_b128 v[128:131], v145 offset:22528
	ds_read_b128 v[132:135], v168 offset:22528
	s_waitcnt lgkmcnt(2)
	v_mfma_f32_16x16x32_bf16 v[52:55], v[100:103], v[112:115], v[52:55]
	s_waitcnt lgkmcnt(1)
	v_mfma_f32_16x16x32_bf16 v[48:51], v[128:131], v[104:107], v[48:51]
	s_waitcnt vmcnt(0)
	s_nop 4
	v_pk_mul_f32 v[54:55], v[54:55], v[58:59]
	v_pk_mul_f32 v[52:53], v[52:53], v[56:57]
	global_store_dwordx4 v[154:155], v[52:55], off offset:128
	global_load_dwordx4 v[52:55], v[136:137], off
	s_waitcnt lgkmcnt(0)
	v_mfma_f32_16x16x32_bf16 v[48:51], v[132:135], v[112:115], v[48:51]
	v_lshl_add_u64 v[56:57], v[150:151], 0, v[160:161]
	v_mfma_f32_16x16x32_bf16 v[24:27], v[68:71], v[64:67], v[24:27]
	v_mfma_f32_16x16x32_bf16 v[16:19], v[60:63], v[108:111], v[16:19]
	s_waitcnt vmcnt(0)
	s_nop 3
	v_pk_mul_f32 v[50:51], v[50:51], v[54:55]
	v_pk_mul_f32 v[48:49], v[48:49], v[52:53]
	global_store_dwordx4 v[154:155], v[48:51], off offset:144
	global_load_dwordx4 v[48:51], v[56:57], off
	ds_read_b128 v[52:55], v145 offset:24576
	ds_read_b128 v[56:59], v168 offset:24576
	s_waitcnt lgkmcnt(1)
	v_mfma_f32_16x16x32_bf16 v[44:47], v[52:55], v[104:107], v[44:47]
	ds_read_b128 v[136:139], v145 offset:26624
	ds_read_b128 v[140:143], v168 offset:26624
	s_waitcnt lgkmcnt(2)
	v_mfma_f32_16x16x32_bf16 v[44:47], v[56:59], v[112:115], v[44:47]
	s_waitcnt lgkmcnt(1)
	v_mfma_f32_16x16x32_bf16 v[40:43], v[136:139], v[104:107], v[40:43]
	s_waitcnt vmcnt(0)
	s_nop 4
	v_pk_mul_f32 v[46:47], v[46:47], v[50:51]
	v_pk_mul_f32 v[44:45], v[44:45], v[48:49]
	global_store_dwordx4 v[154:155], v[44:47], off offset:256
	global_load_dwordx4 v[44:47], v[146:147], off
	s_waitcnt lgkmcnt(0)
	v_mfma_f32_16x16x32_bf16 v[40:43], v[140:143], v[112:115], v[40:43]
	ds_read_b128 v[48:51], v145 offset:28672
	ds_read_b128 v[146:149], v145 offset:30720
	s_waitcnt lgkmcnt(1)
	v_mfma_f32_16x16x32_bf16 v[36:39], v[48:51], v[104:107], v[36:39]
	s_waitcnt vmcnt(0)
	s_nop 2
	v_pk_mul_f32 v[42:43], v[42:43], v[46:47]
	v_pk_mul_f32 v[40:41], v[40:41], v[44:45]
	global_store_dwordx4 v[154:155], v[40:43], off offset:272
	global_load_dwordx4 v[40:43], v[166:167], off
	ds_read_b128 v[44:47], v168 offset:28672
	s_waitcnt lgkmcnt(1)
	v_mfma_f32_16x16x32_bf16 v[32:35], v[146:149], v[104:107], v[32:35]
	ds_read_b128 v[104:107], v168 offset:30720
	v_mov_b32_e32 v167, v73
	v_or_b32_e32 v166, 0x190, v72
	s_waitcnt lgkmcnt(1)
	v_mfma_f32_16x16x32_bf16 v[36:39], v[44:47], v[112:115], v[36:39]
	v_lshl_add_u64 v[116:117], v[150:151], 0, v[166:167]
	s_waitcnt vmcnt(0)
	s_nop 5
	v_pk_mul_f32 v[38:39], v[38:39], v[42:43]
	v_pk_mul_f32 v[36:37], v[36:37], v[40:41]
	global_store_dwordx4 v[154:155], v[36:39], off offset:384
	global_load_dwordx4 v[36:39], v[116:117], off
	v_mul_hi_i32 v40, v99, s39
	v_lshrrev_b32_e32 v41, 31, v40
	v_ashrrev_i32_e32 v40, 11, v40
	v_add_u32_e32 v40, v40, v41
	v_mad_i32_i24 v41, v40, s40, v99
	v_cmp_lt_i32_e32 vcc, s41, v41
	s_waitcnt lgkmcnt(0)
	v_mfma_f32_16x16x32_bf16 v[32:35], v[104:107], v[112:115], v[32:35]
	v_cndmask_b32_e32 v40, 2, v40, vcc
	v_mul_hi_i32_i24_e32 v41, 0x6000, v40
	v_mul_i32_i24_e32 v40, 0x6000, v40
	v_lshl_add_u64 v[40:41], s[94:95], 0, v[40:41]
	v_lshl_add_u64 v[40:41], v[40:41], 0, s[34:35]
	v_lshl_add_u64 v[42:43], v[40:41], 0, v[72:73]
	v_mfma_f32_16x16x32_bf16 v[16:19], v[100:103], v[64:67], v[16:19]
	s_waitcnt vmcnt(0)
	v_pk_mul_f32 v[34:35], v[34:35], v[38:39]
	v_pk_mul_f32 v[32:33], v[32:33], v[36:37]
	global_store_dwordx4 v[154:155], v[32:35], off offset:400
	global_load_dwordx4 v[32:35], v[42:43], off
	v_mul_hi_i32 v36, v99, s38
	v_lshrrev_b32_e32 v37, 31, v36
	v_lshrrev_b32_e32 v36, 11, v36
	v_add_u32_e32 v36, v36, v37
	v_lshl_add_u32 v36, v36, 13, v99
	v_ashrrev_i32_e32 v37, 31, v36
	v_lshl_add_u64 v[36:37], v[36:37], 0, s[8:9]
	v_lshlrev_b64 v[36:37], 12, v[36:37]
	v_lshl_add_u64 v[36:37], s[6:7], 0, v[36:37]
	v_lshl_add_u64 v[36:37], v[36:37], 0, v[72:73]
	v_lshl_add_u64 v[38:39], v[40:41], 0, v[152:153]
	v_mfma_f32_16x16x32_bf16 v[12:15], v[128:131], v[108:111], v[12:15]
	s_waitcnt vmcnt(0)
	v_pk_mul_f32 v[30:31], v[30:31], v[34:35]
	v_pk_mul_f32 v[28:29], v[28:29], v[32:33]
	global_store_dwordx4 v[36:37], v[28:31], off
	global_load_dwordx4 v[28:31], v[38:39], off
	v_lshl_add_u64 v[32:33], v[40:41], 0, v[156:157]
	v_mfma_f32_16x16x32_bf16 v[12:15], v[132:135], v[64:67], v[12:15]
	s_waitcnt vmcnt(0)
	v_pk_mul_f32 v[26:27], v[26:27], v[30:31]
	v_pk_mul_f32 v[24:25], v[24:25], v[28:29]
	global_store_dwordx4 v[36:37], v[24:27], off offset:16
	global_load_dwordx4 v[24:27], v[32:33], off
	v_lshl_add_u64 v[28:29], v[40:41], 0, v[158:159]
	v_mfma_f32_16x16x32_bf16 v[8:11], v[52:55], v[108:111], v[8:11]
	s_waitcnt vmcnt(0)
	v_pk_mul_f32 v[18:19], v[18:19], v[26:27]
	v_pk_mul_f32 v[16:17], v[16:17], v[24:25]
	global_store_dwordx4 v[36:37], v[16:19], off offset:128
	global_load_dwordx4 v[16:19], v[28:29], off
	v_lshl_add_u64 v[24:25], v[40:41], 0, v[160:161]
	v_mfma_f32_16x16x32_bf16 v[8:11], v[56:59], v[64:67], v[8:11]
	s_waitcnt vmcnt(0)
	v_pk_mul_f32 v[14:15], v[14:15], v[18:19]
	v_pk_mul_f32 v[12:13], v[12:13], v[16:17]
	global_store_dwordx4 v[36:37], v[12:15], off offset:144
	global_load_dwordx4 v[12:15], v[24:25], off
	v_lshl_add_u64 v[16:17], v[40:41], 0, v[162:163]
	v_mfma_f32_16x16x32_bf16 v[4:7], v[136:139], v[108:111], v[4:7]
	s_waitcnt vmcnt(0)
	v_pk_mul_f32 v[10:11], v[10:11], v[14:15]
	v_pk_mul_f32 v[8:9], v[8:9], v[12:13]
	global_store_dwordx4 v[36:37], v[8:11], off offset:256
	global_load_dwordx4 v[8:11], v[16:17], off
	v_mfma_f32_16x16x32_bf16 v[4:7], v[140:143], v[64:67], v[4:7]
	v_lshl_add_u64 v[12:13], v[40:41], 0, v[164:165]
	v_mfma_f32_16x16x32_bf16 v[0:3], v[48:51], v[108:111], v[0:3]
	v_mfma_f32_16x16x32_bf16 v[0:3], v[44:47], v[64:67], v[0:3]
	s_waitcnt vmcnt(0)
	s_nop 3
	v_pk_mul_f32 v[6:7], v[6:7], v[10:11]
	v_pk_mul_f32 v[4:5], v[4:5], v[8:9]
	global_store_dwordx4 v[36:37], v[4:7], off offset:272
	global_load_dwordx4 v[4:7], v[12:13], off
	v_lshl_add_u64 v[8:9], v[40:41], 0, v[166:167]
	v_mfma_f32_16x16x32_bf16 v[20:23], v[146:149], v[108:111], v[20:23]
	s_waitcnt vmcnt(0)
	v_pk_mul_f32 v[2:3], v[2:3], v[6:7]
	v_pk_mul_f32 v[0:1], v[0:1], v[4:5]
	global_store_dwordx4 v[36:37], v[0:3], off offset:384
	global_load_dwordx4 v[0:3], v[8:9], off
	v_mfma_f32_16x16x32_bf16 v[4:7], v[104:107], v[64:67], v[20:23]
	s_waitcnt vmcnt(0)
	s_nop 6
	v_pk_mul_f32 v[2:3], v[6:7], v[2:3]
	v_pk_mul_f32 v[0:1], v[4:5], v[0:1]
	global_store_dwordx4 v[36:37], v[0:3], off offset:400
	s_cbranch_scc0 .LBB0_1090

.LBB0_1217:
	s_add_i32 s41, s3, 0x8000
	s_and_b32 s40, s41, 0x8000
	s_add_i32 s40, s40, 0
	s_and_b32 s3, s3, 0x8000
	s_add_i32 s3, s3, 0
	s_add_u32 s86, s3, s87
	s_waitcnt vmcnt(8)
	s_barrier
	v_add3_u32 v145, s3, v87, v88
	v_add3_u32 v186, s3, v88, v89
	v_add3_u32 v187, s3, v87, v90
	v_add3_u32 v188, s3, v89, v90
	ds_read_b128 v[112:115], v186
	ds_read_b128 v[104:107], v145 offset:16384
	ds_read_b128 v[108:111], v145 offset:18432
	ds_read_b128 v[116:119], v186 offset:2048
	ds_read_b128 v[120:123], v145 offset:20480
	ds_read_b128 v[124:127], v145 offset:22528
	ds_read_b128 v[128:131], v145 offset:24576
	ds_read_b128 v[132:135], v145 offset:26624
	ds_read_b128 v[136:139], v145 offset:28672
	ds_read_b128 v[140:143], v145 offset:30720
	ds_read_b128 v[154:157], v188
	ds_read_b128 v[146:149], v187 offset:16384
	ds_read_b128 v[150:153], v187 offset:18432
	ds_read_b128 v[158:161], v188 offset:2048
	ds_read_b128 v[162:165], v187 offset:20480
	ds_read_b128 v[166:169], v187 offset:22528
	ds_read_b128 v[170:173], v187 offset:24576
	ds_read_b128 v[174:177], v187 offset:26624
	ds_read_b128 v[178:181], v187 offset:28672
	ds_read_b128 v[182:185], v187 offset:30720
	s_waitcnt lgkmcnt(15)
	v_mfma_f32_16x16x32_bf16 v[60:63], v[104:107], v[112:115], v[60:63]
	v_mfma_f32_16x16x32_bf16 v[56:59], v[108:111], v[112:115], v[56:59]
	v_mfma_f32_16x16x32_bf16 v[24:27], v[104:107], v[116:119], v[24:27]
	v_mfma_f32_16x16x32_bf16 v[20:23], v[108:111], v[116:119], v[20:23]
	v_mfma_f32_16x16x32_bf16 v[52:55], v[120:123], v[112:115], v[52:55]
	v_mfma_f32_16x16x32_bf16 v[16:19], v[120:123], v[116:119], v[16:19]
	s_waitcnt lgkmcnt(14)
	v_mfma_f32_16x16x32_bf16 v[48:51], v[124:127], v[112:115], v[48:51]
	v_mfma_f32_16x16x32_bf16 v[12:15], v[124:127], v[116:119], v[12:15]
	s_waitcnt lgkmcnt(13)
	v_mfma_f32_16x16x32_bf16 v[44:47], v[128:131], v[112:115], v[44:47]
	v_mfma_f32_16x16x32_bf16 v[8:11], v[128:131], v[116:119], v[8:11]
	s_waitcnt lgkmcnt(12)
	v_mfma_f32_16x16x32_bf16 v[36:39], v[132:135], v[112:115], v[36:39]
	v_mfma_f32_16x16x32_bf16 v[4:7], v[132:135], v[116:119], v[4:7]
	s_waitcnt lgkmcnt(11)
	v_mfma_f32_16x16x32_bf16 v[32:35], v[136:139], v[112:115], v[32:35]
	v_mfma_f32_16x16x32_bf16 v[0:3], v[136:139], v[116:119], v[0:3]
	s_waitcnt lgkmcnt(10)
	v_mfma_f32_16x16x32_bf16 v[28:31], v[140:143], v[112:115], v[28:31]
	v_mfma_f32_16x16x32_bf16 v[40:43], v[140:143], v[116:119], v[40:43]
	s_waitcnt lgkmcnt(0)
	s_barrier
	s_cmpk_eq_i32 s0, 0x700
	s_cbranch_scc1 .Lgskip_1217
	s_mov_b32 m0, s86
	s_nop 0
	global_load_lds_dwordx4 v244, s[96:97]
	s_add_u32 m0, s86, 0x4000
	s_nop 0
	global_load_lds_dwordx4 v245, s[88:89]
	s_add_u32 m0, s86, 0x1000
	s_nop 0
	global_load_lds_dwordx4 v246, s[96:97]
	s_add_u32 m0, s86, 0x5000
	s_nop 0
	global_load_lds_dwordx4 v247, s[88:89]
	s_add_u32 m0, s86, 0x2000
	s_nop 0
	global_load_lds_dwordx4 v248, s[96:97]
	s_add_u32 m0, s86, 0x6000
	s_nop 0
	global_load_lds_dwordx4 v249, s[88:89]
	s_add_u32 m0, s86, 0x3000
	s_nop 0
	global_load_lds_dwordx4 v250, s[96:97]
	s_add_u32 m0, s86, 0x7000
	s_nop 0
	global_load_lds_dwordx4 v251, s[88:89]
	s_add_u32 s96, s96, 0x80
	s_addc_u32 s97, s97, 0
	s_add_u32 s88, s88, 0x80
	s_addc_u32 s89, s89, 0
.Lgskip_1217:
	s_add_u32 s0, s0, 0x80
	s_addc_u32 s1, s1, 0
	s_cmpk_eq_i32 s0, 0x780
	s_mov_b32 s3, s41
	v_mfma_f32_16x16x32_bf16 v[60:63], v[146:149], v[154:157], v[60:63]
	v_mfma_f32_16x16x32_bf16 v[56:59], v[150:153], v[154:157], v[56:59]
	v_mfma_f32_16x16x32_bf16 v[24:27], v[146:149], v[158:161], v[24:27]
	v_mfma_f32_16x16x32_bf16 v[20:23], v[150:153], v[158:161], v[20:23]
	v_mfma_f32_16x16x32_bf16 v[52:55], v[162:165], v[154:157], v[52:55]
	v_mfma_f32_16x16x32_bf16 v[16:19], v[162:165], v[158:161], v[16:19]
	v_mfma_f32_16x16x32_bf16 v[48:51], v[166:169], v[154:157], v[48:51]
	v_mfma_f32_16x16x32_bf16 v[12:15], v[166:169], v[158:161], v[12:15]
	v_mfma_f32_16x16x32_bf16 v[44:47], v[170:173], v[154:157], v[44:47]
	v_mfma_f32_16x16x32_bf16 v[8:11], v[170:173], v[158:161], v[8:11]
	v_mfma_f32_16x16x32_bf16 v[36:39], v[174:177], v[154:157], v[36:39]
	v_mfma_f32_16x16x32_bf16 v[4:7], v[174:177], v[158:161], v[4:7]
	v_mfma_f32_16x16x32_bf16 v[32:35], v[178:181], v[154:157], v[32:35]
	v_mfma_f32_16x16x32_bf16 v[0:3], v[178:181], v[158:161], v[0:3]
	v_mfma_f32_16x16x32_bf16 v[28:31], v[182:185], v[154:157], v[28:31]
	v_mfma_f32_16x16x32_bf16 v[40:43], v[182:185], v[158:161], v[40:43]
	s_cbranch_scc0 .LBB0_1217
	v_add_u32_e32 v64, s40, v87
	v_add_u32_e32 v103, v64, v88
	v_add3_u32 v112, s40, v88, v89
	s_waitcnt vmcnt(0)
	s_barrier
	ds_read_b128 v[82:85], v103 offset:16384
	ds_read_b128 v[104:107], v103 offset:18432
	ds_read_b128 v[108:111], v112
	ds_read_b128 v[112:115], v112 offset:2048
	ds_read_b128 v[116:119], v103 offset:20480
	ds_read_b128 v[120:123], v103 offset:22528
	ds_read_b128 v[124:127], v103 offset:24576
	ds_read_b128 v[128:131], v103 offset:26624
	ds_read_b128 v[132:135], v103 offset:28672
	ds_read_b128 v[136:139], v103 offset:30720
	v_add_u32_e32 v64, v64, v90
	s_waitcnt lgkmcnt(7)
	v_mfma_f32_16x16x32_bf16 v[60:63], v[82:85], v[108:111], v[60:63]
	s_mul_hi_i32 s0, s2, 0x3e0f83e1
	s_lshr_b32 s1, s0, 31
	s_ashr_i32 s56, s0, 4
	v_mfma_f32_16x16x32_bf16 v[56:59], v[104:107], v[108:111], v[56:59]
	s_add_i32 s56, s56, s1
	s_cmp_gt_i32 s39, 11
	s_cselect_b64 s[0:1], -1, 0
	s_waitcnt lgkmcnt(4)
	v_mfma_f32_16x16x32_bf16 v[48:51], v[120:123], v[108:111], v[48:51]
	s_lshl_b32 s53, s2, 7
	s_cmp_lt_i32 s39, 12
	s_mul_i32 s54, s56, 0xffffdf00
	s_waitcnt lgkmcnt(3)
	v_mfma_f32_16x16x32_bf16 v[44:47], v[124:127], v[108:111], v[44:47]
	s_waitcnt lgkmcnt(2)
	v_mfma_f32_16x16x32_bf16 v[36:39], v[128:131], v[108:111], v[36:39]
	s_waitcnt lgkmcnt(1)
	v_mfma_f32_16x16x32_bf16 v[32:35], v[132:135], v[108:111], v[32:35]
	s_waitcnt lgkmcnt(0)
	v_mfma_f32_16x16x32_bf16 v[28:31], v[136:139], v[108:111], v[28:31]
	v_mfma_f32_16x16x32_bf16 v[24:27], v[82:85], v[112:115], v[24:27]
	ds_read_b128 v[82:85], v64 offset:16384
	v_mfma_f32_16x16x32_bf16 v[52:55], v[116:119], v[108:111], v[52:55]
	v_mfma_f32_16x16x32_bf16 v[20:23], v[104:107], v[112:115], v[20:23]
	v_mfma_f32_16x16x32_bf16 v[16:19], v[116:119], v[112:115], v[16:19]
	v_mfma_f32_16x16x32_bf16 v[12:15], v[120:123], v[112:115], v[12:15]
	v_mfma_f32_16x16x32_bf16 v[8:11], v[124:127], v[112:115], v[8:11]
	v_mfma_f32_16x16x32_bf16 v[4:7], v[128:131], v[112:115], v[4:7]
	v_mfma_f32_16x16x32_bf16 v[0:3], v[132:135], v[112:115], v[0:3]
	v_mfma_f32_16x16x32_bf16 v[104:107], v[136:139], v[112:115], v[40:43]
	s_nop 2
	v_add3_u32 v40, s40, v90, v89
	ds_read_b128 v[108:111], v64 offset:18432
	ds_read_b128 v[112:115], v40
	ds_read_b128 v[116:119], v40 offset:2048
	ds_read_b128 v[120:123], v64 offset:20480
	ds_read_b128 v[124:127], v64 offset:22528
	ds_read_b128 v[128:131], v64 offset:24576
	ds_read_b128 v[132:135], v64 offset:26624
	ds_read_b128 v[136:139], v64 offset:28672
	ds_read_b128 v[140:143], v64 offset:30720
	s_waitcnt lgkmcnt(7)
	v_mfma_f32_16x16x32_bf16 v[60:63], v[82:85], v[112:115], v[60:63]
	v_mfma_f32_16x16x32_bf16 v[56:59], v[108:111], v[112:115], v[56:59]
	s_waitcnt lgkmcnt(5)
	v_mfma_f32_16x16x32_bf16 v[52:55], v[120:123], v[112:115], v[52:55]
	s_waitcnt lgkmcnt(4)
	v_mfma_f32_16x16x32_bf16 v[48:51], v[124:127], v[112:115], v[48:51]
	s_waitcnt lgkmcnt(3)
	v_mfma_f32_16x16x32_bf16 v[44:47], v[128:131], v[112:115], v[44:47]
	s_waitcnt lgkmcnt(2)
	v_mfma_f32_16x16x32_bf16 v[40:43], v[132:135], v[112:115], v[36:39]
	s_waitcnt lgkmcnt(1)
	v_mfma_f32_16x16x32_bf16 v[36:39], v[136:139], v[112:115], v[32:35]
	s_waitcnt lgkmcnt(0)
	v_mfma_f32_16x16x32_bf16 v[32:35], v[140:143], v[112:115], v[28:31]
	v_mfma_f32_16x16x32_bf16 v[28:31], v[82:85], v[116:119], v[24:27]
	v_mfma_f32_16x16x32_bf16 v[24:27], v[108:111], v[116:119], v[20:23]
	v_mfma_f32_16x16x32_bf16 v[20:23], v[120:123], v[116:119], v[16:19]
	v_mfma_f32_16x16x32_bf16 v[16:19], v[124:127], v[116:119], v[12:15]
	v_mfma_f32_16x16x32_bf16 v[12:15], v[128:131], v[116:119], v[8:11]
	v_mfma_f32_16x16x32_bf16 v[8:11], v[132:135], v[116:119], v[4:7]
	v_mfma_f32_16x16x32_bf16 v[4:7], v[136:139], v[116:119], v[0:3]
	v_mfma_f32_16x16x32_bf16 v[0:3], v[140:143], v[116:119], v[104:107]
	s_cbranch_scc0 .LBB0_1224
	s_add_i32 s40, s54, s53
	v_add_u32_e32 v64, s40, v70
	v_cmp_lt_i32_e32 vcc, s48, v64
	s_and_saveexec_b64 s[2:3], vcc
	s_cbranch_execz .LBB0_1221
	v_lshl_add_u32 v64, v64, 5, v102
	v_lshlrev_b64 v[108:109], 2, v[64:65]
	v_lshl_add_u64 v[104:105], v[76:77], 0, v[108:109]
	global_load_dwordx4 v[82:85], v[104:105], off
	s_nop 0
	global_load_dwordx4 v[104:107], v[104:105], off offset:16
	v_lshl_add_u64 v[112:113], v[74:75], 0, v[108:109]
	global_load_dwordx4 v[108:111], v[112:113], off
	s_nop 0
	global_load_dwordx4 v[112:115], v[112:113], off offset:16
	s_waitcnt vmcnt(3)
	v_pk_mul_f32 v[116:117], v[54:55], v[84:85]
	v_pk_mul_f32 v[118:119], v[52:53], v[82:83]
	v_pk_mul_f32 v[120:121], v[62:63], v[84:85]
	v_pk_mul_f32 v[122:123], v[60:61], v[82:83]
	s_waitcnt vmcnt(2)
	v_pk_mul_f32 v[124:125], v[50:51], v[106:107]
	v_pk_mul_f32 v[126:127], v[48:49], v[104:105]
	v_pk_mul_f32 v[128:129], v[58:59], v[106:107]
	v_pk_mul_f32 v[130:131], v[56:57], v[104:105]
	v_pk_mul_f32 v[132:133], v[38:39], v[84:85]
	v_pk_mul_f32 v[134:135], v[36:37], v[82:83]
	v_pk_mul_f32 v[84:85], v[46:47], v[84:85]
	v_pk_mul_f32 v[82:83], v[44:45], v[82:83]
	v_pk_mul_f32 v[136:137], v[34:35], v[106:107]
	v_pk_mul_f32 v[138:139], v[32:33], v[104:105]
	v_pk_mul_f32 v[106:107], v[42:43], v[106:107]
	v_pk_mul_f32 v[104:105], v[40:41], v[104:105]
	s_waitcnt vmcnt(1)
	v_pk_fma_f32 v[62:63], v[62:63], v[110:111], v[116:117] neg_lo:[0,0,1] neg_hi:[0,0,1]
	v_pk_fma_f32 v[60:61], v[60:61], v[108:109], v[118:119] neg_lo:[0,0,1] neg_hi:[0,0,1]
	v_pk_fma_f32 v[54:55], v[54:55], v[110:111], v[120:121]
	v_pk_fma_f32 v[52:53], v[52:53], v[108:109], v[122:123]
	s_waitcnt vmcnt(0)
	v_pk_fma_f32 v[58:59], v[58:59], v[114:115], v[124:125] neg_lo:[0,0,1] neg_hi:[0,0,1]
	v_pk_fma_f32 v[56:57], v[56:57], v[112:113], v[126:127] neg_lo:[0,0,1] neg_hi:[0,0,1]
	v_pk_fma_f32 v[50:51], v[50:51], v[114:115], v[128:129]
	v_pk_fma_f32 v[48:49], v[48:49], v[112:113], v[130:131]
	v_pk_fma_f32 v[46:47], v[46:47], v[110:111], v[132:133] neg_lo:[0,0,1] neg_hi:[0,0,1]
	v_pk_fma_f32 v[44:45], v[44:45], v[108:109], v[134:135] neg_lo:[0,0,1] neg_hi:[0,0,1]
	v_pk_fma_f32 v[38:39], v[38:39], v[110:111], v[84:85]
	v_pk_fma_f32 v[36:37], v[36:37], v[108:109], v[82:83]
	v_pk_fma_f32 v[42:43], v[42:43], v[114:115], v[136:137] neg_lo:[0,0,1] neg_hi:[0,0,1]
	v_pk_fma_f32 v[40:41], v[40:41], v[112:113], v[138:139] neg_lo:[0,0,1] neg_hi:[0,0,1]
	v_pk_fma_f32 v[34:35], v[34:35], v[114:115], v[106:107]
	v_pk_fma_f32 v[32:33], v[32:33], v[112:113], v[104:105]

.LBB0_1615:
	s_add_i32 s41, s39, 0x8000
	s_and_b32 s40, s41, 0x8000
	s_add_i32 s40, s40, 0
	s_and_b32 s39, s39, 0x8000
	s_add_i32 s39, s39, 0
	s_add_u32 s86, s39, s87
	s_waitcnt vmcnt(8)
	s_barrier
	v_add3_u32 v145, s39, v84, v85
	v_add3_u32 v178, s39, v85, v86
	v_add3_u32 v179, s39, v84, v87
	v_add3_u32 v180, s39, v86, v87
	ds_read_b128 v[104:107], v178
	ds_read_b128 v[76:79], v145 offset:16384
	ds_read_b128 v[100:103], v145 offset:18432
	ds_read_b128 v[108:111], v178 offset:2048
	ds_read_b128 v[112:115], v145 offset:20480
	ds_read_b128 v[116:119], v145 offset:22528
	ds_read_b128 v[120:123], v145 offset:24576
	ds_read_b128 v[124:127], v145 offset:26624
	ds_read_b128 v[128:131], v145 offset:28672
	ds_read_b128 v[132:135], v145 offset:30720
	ds_read_b128 v[146:149], v180
	ds_read_b128 v[136:139], v179 offset:16384
	ds_read_b128 v[140:143], v179 offset:18432
	ds_read_b128 v[150:153], v180 offset:2048
	ds_read_b128 v[154:157], v179 offset:20480
	ds_read_b128 v[158:161], v179 offset:22528
	ds_read_b128 v[162:165], v179 offset:24576
	ds_read_b128 v[166:169], v179 offset:26624
	ds_read_b128 v[170:173], v179 offset:28672
	ds_read_b128 v[174:177], v179 offset:30720
	s_waitcnt lgkmcnt(15)
	v_mfma_f32_16x16x32_bf16 v[60:63], v[76:79], v[104:107], v[60:63]
	v_mfma_f32_16x16x32_bf16 v[56:59], v[100:103], v[104:107], v[56:59]
	v_mfma_f32_16x16x32_bf16 v[24:27], v[76:79], v[108:111], v[24:27]
	v_mfma_f32_16x16x32_bf16 v[20:23], v[100:103], v[108:111], v[20:23]
	v_mfma_f32_16x16x32_bf16 v[52:55], v[112:115], v[104:107], v[52:55]
	v_mfma_f32_16x16x32_bf16 v[16:19], v[112:115], v[108:111], v[16:19]
	s_waitcnt lgkmcnt(14)
	v_mfma_f32_16x16x32_bf16 v[48:51], v[116:119], v[104:107], v[48:51]
	v_mfma_f32_16x16x32_bf16 v[12:15], v[116:119], v[108:111], v[12:15]
	s_waitcnt lgkmcnt(13)
	v_mfma_f32_16x16x32_bf16 v[44:47], v[120:123], v[104:107], v[44:47]
	v_mfma_f32_16x16x32_bf16 v[8:11], v[120:123], v[108:111], v[8:11]
	s_waitcnt lgkmcnt(12)
	v_mfma_f32_16x16x32_bf16 v[40:43], v[124:127], v[104:107], v[40:43]
	v_mfma_f32_16x16x32_bf16 v[4:7], v[124:127], v[108:111], v[4:7]
	s_waitcnt lgkmcnt(11)
	v_mfma_f32_16x16x32_bf16 v[32:35], v[128:131], v[104:107], v[32:35]
	v_mfma_f32_16x16x32_bf16 v[0:3], v[128:131], v[108:111], v[0:3]
	s_waitcnt lgkmcnt(10)
	v_mfma_f32_16x16x32_bf16 v[28:31], v[132:135], v[104:107], v[28:31]
	v_mfma_f32_16x16x32_bf16 v[36:39], v[132:135], v[108:111], v[36:39]
	s_waitcnt lgkmcnt(0)
	s_barrier
	s_cmpk_eq_i32 s28, 0x700
	s_cbranch_scc1 .Lgskip_1615
	s_mov_b32 m0, s86
	s_nop 0
	global_load_lds_dwordx4 v244, s[96:97]
	s_add_u32 m0, s86, 0x4000
	s_nop 0
	global_load_lds_dwordx4 v245, s[88:89]
	s_add_u32 m0, s86, 0x1000
	s_nop 0
	global_load_lds_dwordx4 v246, s[96:97]
	s_add_u32 m0, s86, 0x5000
	s_nop 0
	global_load_lds_dwordx4 v247, s[88:89]
	s_add_u32 m0, s86, 0x2000
	s_nop 0
	global_load_lds_dwordx4 v248, s[96:97]
	s_add_u32 m0, s86, 0x6000
	s_nop 0
	global_load_lds_dwordx4 v249, s[88:89]
	s_add_u32 m0, s86, 0x3000
	s_nop 0
	global_load_lds_dwordx4 v250, s[96:97]
	s_add_u32 m0, s86, 0x7000
	s_nop 0
	global_load_lds_dwordx4 v251, s[88:89]
	s_add_u32 s96, s96, 0x80
	s_addc_u32 s97, s97, 0
	s_add_u32 s88, s88, 0x80
	s_addc_u32 s89, s89, 0
.Lgskip_1615:
	s_add_u32 s28, s28, 0x80
	s_addc_u32 s29, s29, 0
	s_cmpk_eq_i32 s28, 0x780
	s_mov_b32 s39, s41
	v_mfma_f32_16x16x32_bf16 v[60:63], v[136:139], v[146:149], v[60:63]
	v_mfma_f32_16x16x32_bf16 v[56:59], v[140:143], v[146:149], v[56:59]
	v_mfma_f32_16x16x32_bf16 v[24:27], v[136:139], v[150:153], v[24:27]
	v_mfma_f32_16x16x32_bf16 v[20:23], v[140:143], v[150:153], v[20:23]
	v_mfma_f32_16x16x32_bf16 v[52:55], v[154:157], v[146:149], v[52:55]
	v_mfma_f32_16x16x32_bf16 v[16:19], v[154:157], v[150:153], v[16:19]
	v_mfma_f32_16x16x32_bf16 v[48:51], v[158:161], v[146:149], v[48:51]
	v_mfma_f32_16x16x32_bf16 v[12:15], v[158:161], v[150:153], v[12:15]
	v_mfma_f32_16x16x32_bf16 v[44:47], v[162:165], v[146:149], v[44:47]
	v_mfma_f32_16x16x32_bf16 v[8:11], v[162:165], v[150:153], v[8:11]
	v_mfma_f32_16x16x32_bf16 v[40:43], v[166:169], v[146:149], v[40:43]
	v_mfma_f32_16x16x32_bf16 v[4:7], v[166:169], v[150:153], v[4:7]
	v_mfma_f32_16x16x32_bf16 v[32:35], v[170:173], v[146:149], v[32:35]
	v_mfma_f32_16x16x32_bf16 v[0:3], v[170:173], v[150:153], v[0:3]
	v_mfma_f32_16x16x32_bf16 v[28:31], v[174:177], v[146:149], v[28:31]
	v_mfma_f32_16x16x32_bf16 v[36:39], v[174:177], v[150:153], v[36:39]
	s_cbranch_scc0 .LBB0_1615
	v_add_u32_e32 v80, s40, v84
	v_add_u32_e32 v81, v80, v85
	s_waitcnt vmcnt(0)
	s_barrier
	ds_read_b128 v[72:75], v81 offset:16384
	v_add3_u32 v99, s40, v85, v86
	ds_read_b128 v[76:79], v81 offset:18432
	ds_read_b128 v[100:103], v99
	ds_read_b128 v[104:107], v99 offset:2048
	ds_read_b128 v[108:111], v81 offset:20480
	ds_read_b128 v[112:115], v81 offset:22528
	ds_read_b128 v[116:119], v81 offset:24576
	ds_read_b128 v[120:123], v81 offset:26624
	ds_read_b128 v[124:127], v81 offset:28672
	ds_read_b128 v[128:131], v81 offset:30720
	v_add_u32_e32 v80, v80, v87
	s_waitcnt lgkmcnt(7)
	v_mfma_f32_16x16x32_bf16 v[60:63], v[72:75], v[100:103], v[60:63]
	s_lshl_b32 s38, s38, 7
	v_mfma_f32_16x16x32_bf16 v[56:59], v[76:79], v[100:103], v[56:59]
	s_waitcnt lgkmcnt(4)
	v_mfma_f32_16x16x32_bf16 v[48:51], v[112:115], v[100:103], v[48:51]
	s_waitcnt lgkmcnt(3)
	v_mfma_f32_16x16x32_bf16 v[44:47], v[116:119], v[100:103], v[44:47]
	s_waitcnt lgkmcnt(2)
	v_mfma_f32_16x16x32_bf16 v[40:43], v[120:123], v[100:103], v[40:43]
	s_waitcnt lgkmcnt(1)
	v_mfma_f32_16x16x32_bf16 v[32:35], v[124:127], v[100:103], v[32:35]
	s_waitcnt lgkmcnt(0)
	v_mfma_f32_16x16x32_bf16 v[28:31], v[128:131], v[100:103], v[28:31]
	v_mfma_f32_16x16x32_bf16 v[24:27], v[72:75], v[104:107], v[24:27]
	ds_read_b128 v[72:75], v80 offset:16384
	v_mfma_f32_16x16x32_bf16 v[52:55], v[108:111], v[100:103], v[52:55]
	v_mfma_f32_16x16x32_bf16 v[20:23], v[76:79], v[104:107], v[20:23]
	v_mfma_f32_16x16x32_bf16 v[16:19], v[108:111], v[104:107], v[16:19]
	v_mfma_f32_16x16x32_bf16 v[12:15], v[112:115], v[104:107], v[12:15]
	v_mfma_f32_16x16x32_bf16 v[8:11], v[116:119], v[104:107], v[8:11]
	v_mfma_f32_16x16x32_bf16 v[4:7], v[120:123], v[104:107], v[4:7]
	v_mfma_f32_16x16x32_bf16 v[0:3], v[124:127], v[104:107], v[0:3]
	v_mfma_f32_16x16x32_bf16 v[100:103], v[128:131], v[104:107], v[36:39]
	s_nop 2
	v_add3_u32 v36, s40, v87, v86
	ds_read_b128 v[76:79], v80 offset:18432
	ds_read_b128 v[104:107], v36
	ds_read_b128 v[108:111], v36 offset:2048
	ds_read_b128 v[128:131], v80 offset:28672
	ds_read_b128 v[132:135], v80 offset:30720
	ds_read_b128 v[112:115], v80 offset:20480
	ds_read_b128 v[116:119], v80 offset:22528
	ds_read_b128 v[120:123], v80 offset:24576
	ds_read_b128 v[124:127], v80 offset:26624
	s_waitcnt lgkmcnt(7)
	v_mfma_f32_16x16x32_bf16 v[60:63], v[72:75], v[104:107], v[60:63]
	s_waitcnt lgkmcnt(5)
	v_mfma_f32_16x16x32_bf16 v[36:39], v[128:131], v[104:107], v[32:35]
	s_waitcnt lgkmcnt(4)
	v_mfma_f32_16x16x32_bf16 v[32:35], v[132:135], v[104:107], v[28:31]
	v_mfma_f32_16x16x32_bf16 v[28:31], v[72:75], v[108:111], v[24:27]
	v_add_u32_e32 v72, s38, v83
	v_mul_hi_i32 v73, v72, s31
	v_mfma_f32_16x16x32_bf16 v[24:27], v[76:79], v[108:111], v[20:23]
	s_waitcnt lgkmcnt(3)
	v_mfma_f32_16x16x32_bf16 v[20:23], v[112:115], v[108:111], v[16:19]
	s_waitcnt lgkmcnt(2)
	v_mfma_f32_16x16x32_bf16 v[16:19], v[116:119], v[108:111], v[12:15]
	s_waitcnt lgkmcnt(1)
	v_mfma_f32_16x16x32_bf16 v[12:15], v[120:123], v[108:111], v[8:11]
	s_waitcnt lgkmcnt(0)
	v_mfma_f32_16x16x32_bf16 v[8:11], v[124:127], v[108:111], v[4:7]
	s_nop 2
	v_lshrrev_b32_e32 v4, 31, v73
	v_ashrrev_i32_e32 v5, 11, v73
	v_mfma_f32_16x16x32_bf16 v[56:59], v[76:79], v[104:107], v[56:59]
	v_add_u32_e32 v73, v5, v4
	v_mad_i32_i24 v78, v73, s33, v72
	v_lshlrev_b32_e32 v75, 13, v73
	v_mfma_f32_16x16x32_bf16 v[52:55], v[112:115], v[104:107], v[52:55]
	v_cmp_lt_i32_e32 vcc, s34, v78
	v_add3_u32 v74, v75, v78, s35
	v_mfma_f32_16x16x32_bf16 v[48:51], v[116:119], v[104:107], v[48:51]
	v_mfma_f32_16x16x32_bf16 v[44:47], v[120:123], v[104:107], v[44:47]
	v_mfma_f32_16x16x32_bf16 v[40:43], v[124:127], v[104:107], v[40:43]
	v_mfma_f32_16x16x32_bf16 v[4:7], v[128:131], v[108:111], v[0:3]
	v_mfma_f32_16x16x32_bf16 v[0:3], v[132:135], v[108:111], v[100:103]
	s_and_saveexec_b64 s[28:29], vcc
	s_xor_b64 s[28:29], exec, s[28:29]
	v_add3_u32 v72, v75, v78, s35
	s_or_saveexec_b64 s[28:29], s[28:29]
	v_mov_b64_e32 v[76:77], s[92:93]
	v_lshl_add_u32 v75, v73, 8, v78
	s_xor_b64 exec, exec, s[28:29]
	v_lshl_add_u32 v72, v73, 8, v78
	v_mov_b64_e32 v[76:77], s[2:3]
	s_or_b64 exec, exec, s[28:29]
	s_and_saveexec_b64 s[28:29], vcc
	s_xor_b64 s[28:29], exec, s[28:29]
	s_cbranch_execz .LBB0_1622
	v_add_u32_e32 v73, 3, v73
	v_mul_hi_i32_i24_e32 v79, 0x6000, v73
	v_mul_i32_i24_e32 v78, 0x6000, v73
	s_or_saveexec_b64 s[28:29], s[28:29]
	v_mov_b64_e32 v[80:81], s[92:93]
	s_xor_b64 exec, exec, s[28:29]
	s_cbranch_execnz .LBB0_1623
	s_branch .LBB0_1624

.LBB0_1759:
	s_add_i32 s36, s34, 0x8000
	s_and_b32 s35, s36, 0x8000
	s_add_i32 s35, s35, 0
	s_and_b32 s34, s34, 0x8000
	s_add_i32 s34, s34, 0
	s_add_u32 s86, s34, s87
	s_waitcnt vmcnt(8)
	s_barrier
	v_add3_u32 v143, s34, v80, v81
	v_add3_u32 v145, s34, v81, v82
	v_add3_u32 v206, s34, v80, v83
	v_add3_u32 v207, s34, v82, v83
	ds_read_b128 v[102:105], v145
	ds_read_b128 v[94:97], v143 offset:16384
	ds_read_b128 v[98:101], v143 offset:18432
	ds_read_b128 v[106:109], v145 offset:2048
	ds_read_b128 v[110:113], v143 offset:20480
	ds_read_b128 v[114:117], v143 offset:22528
	ds_read_b128 v[118:121], v143 offset:24576
	ds_read_b128 v[122:125], v143 offset:26624
	ds_read_b128 v[126:129], v143 offset:28672
	ds_read_b128 v[130:133], v143 offset:30720
	ds_read_b128 v[174:177], v207
	ds_read_b128 v[166:169], v206 offset:16384
	ds_read_b128 v[170:173], v206 offset:18432
	ds_read_b128 v[178:181], v207 offset:2048
	ds_read_b128 v[182:185], v206 offset:20480
	ds_read_b128 v[186:189], v206 offset:22528
	ds_read_b128 v[190:193], v206 offset:24576
	ds_read_b128 v[194:197], v206 offset:26624
	ds_read_b128 v[198:201], v206 offset:28672
	ds_read_b128 v[202:205], v206 offset:30720
	s_waitcnt lgkmcnt(15)
	v_mfma_f32_16x16x32_bf16 v[60:63], v[94:97], v[102:105], v[60:63]
	v_mfma_f32_16x16x32_bf16 v[56:59], v[98:101], v[102:105], v[56:59]
	v_mfma_f32_16x16x32_bf16 v[28:31], v[94:97], v[106:109], v[28:31]
	v_mfma_f32_16x16x32_bf16 v[24:27], v[98:101], v[106:109], v[24:27]
	v_mfma_f32_16x16x32_bf16 v[52:55], v[110:113], v[102:105], v[52:55]
	v_mfma_f32_16x16x32_bf16 v[20:23], v[110:113], v[106:109], v[20:23]
	s_waitcnt lgkmcnt(14)
	v_mfma_f32_16x16x32_bf16 v[48:51], v[114:117], v[102:105], v[48:51]
	v_mfma_f32_16x16x32_bf16 v[12:15], v[114:117], v[106:109], v[12:15]
	s_waitcnt lgkmcnt(13)
	v_mfma_f32_16x16x32_bf16 v[44:47], v[118:121], v[102:105], v[44:47]
	v_mfma_f32_16x16x32_bf16 v[8:11], v[118:121], v[106:109], v[8:11]
	s_waitcnt lgkmcnt(12)
	v_mfma_f32_16x16x32_bf16 v[40:43], v[122:125], v[102:105], v[40:43]
	v_mfma_f32_16x16x32_bf16 v[4:7], v[122:125], v[106:109], v[4:7]
	s_waitcnt lgkmcnt(11)
	v_mfma_f32_16x16x32_bf16 v[36:39], v[126:129], v[102:105], v[36:39]
	v_mfma_f32_16x16x32_bf16 v[0:3], v[126:129], v[106:109], v[0:3]
	s_waitcnt lgkmcnt(10)
	v_mfma_f32_16x16x32_bf16 v[32:35], v[130:133], v[102:105], v[32:35]
	v_mfma_f32_16x16x32_bf16 v[16:19], v[130:133], v[106:109], v[16:19]
	s_waitcnt lgkmcnt(0)
	s_barrier
	s_cmpk_eq_i32 s26, 0x700
	s_cbranch_scc1 .Lgskip_1759
	s_mov_b32 m0, s86
	s_nop 0
	global_load_lds_dwordx4 v244, s[96:97]
	s_add_u32 m0, s86, 0x4000
	s_nop 0
	global_load_lds_dwordx4 v245, s[88:89]
	s_add_u32 m0, s86, 0x1000
	s_nop 0
	global_load_lds_dwordx4 v246, s[96:97]
	s_add_u32 m0, s86, 0x5000
	s_nop 0
	global_load_lds_dwordx4 v247, s[88:89]
	s_add_u32 m0, s86, 0x2000
	s_nop 0
	global_load_lds_dwordx4 v248, s[96:97]
	s_add_u32 m0, s86, 0x6000
	s_nop 0
	global_load_lds_dwordx4 v249, s[88:89]
	s_add_u32 m0, s86, 0x3000
	s_nop 0
	global_load_lds_dwordx4 v250, s[96:97]
	s_add_u32 m0, s86, 0x7000
	s_nop 0
	global_load_lds_dwordx4 v251, s[88:89]
	s_add_u32 s96, s96, 0x80
	s_addc_u32 s97, s97, 0
	s_add_u32 s88, s88, 0x80
	s_addc_u32 s89, s89, 0
.Lgskip_1759:
	s_add_u32 s26, s26, 0x80
	s_addc_u32 s27, s27, 0
	s_cmpk_eq_i32 s26, 0x780
	s_mov_b32 s34, s36
	v_mfma_f32_16x16x32_bf16 v[60:63], v[166:169], v[174:177], v[60:63]
	v_mfma_f32_16x16x32_bf16 v[56:59], v[170:173], v[174:177], v[56:59]
	v_mfma_f32_16x16x32_bf16 v[28:31], v[166:169], v[178:181], v[28:31]
	v_mfma_f32_16x16x32_bf16 v[24:27], v[170:173], v[178:181], v[24:27]
	v_mfma_f32_16x16x32_bf16 v[52:55], v[182:185], v[174:177], v[52:55]
	v_mfma_f32_16x16x32_bf16 v[20:23], v[182:185], v[178:181], v[20:23]
	v_mfma_f32_16x16x32_bf16 v[48:51], v[186:189], v[174:177], v[48:51]
	v_mfma_f32_16x16x32_bf16 v[12:15], v[186:189], v[178:181], v[12:15]
	v_mfma_f32_16x16x32_bf16 v[44:47], v[190:193], v[174:177], v[44:47]
	v_mfma_f32_16x16x32_bf16 v[8:11], v[190:193], v[178:181], v[8:11]
	v_mfma_f32_16x16x32_bf16 v[40:43], v[194:197], v[174:177], v[40:43]
	v_mfma_f32_16x16x32_bf16 v[4:7], v[194:197], v[178:181], v[4:7]
	v_mfma_f32_16x16x32_bf16 v[36:39], v[198:201], v[174:177], v[36:39]
	v_mfma_f32_16x16x32_bf16 v[0:3], v[198:201], v[178:181], v[0:3]
	v_mfma_f32_16x16x32_bf16 v[32:35], v[202:205], v[174:177], v[32:35]
	v_mfma_f32_16x16x32_bf16 v[16:19], v[202:205], v[178:181], v[16:19]
	s_cbranch_scc0 .LBB0_1759
	v_add_u32_e32 v138, s35, v80
	v_add_u32_e32 v126, v138, v81
	s_waitcnt vmcnt(0)
	s_barrier
	ds_read_b128 v[74:77], v126 offset:16384
	v_add3_u32 v102, s35, v81, v82
	ds_read_b128 v[94:97], v102
	ds_read_b128 v[98:101], v126 offset:18432
	ds_read_b128 v[102:105], v102 offset:2048
	ds_read_b128 v[106:109], v126 offset:20480
	ds_read_b128 v[110:113], v126 offset:22528
	ds_read_b128 v[114:117], v126 offset:24576
	ds_read_b128 v[118:121], v126 offset:26624
	v_add3_u32 v134, s35, v83, v82
	v_add_u32_e32 v142, v138, v83
	ds_read_b128 v[122:125], v126 offset:28672
	ds_read_b128 v[126:129], v126 offset:30720
	ds_read_b128 v[130:133], v134
	ds_read_b128 v[134:137], v134 offset:2048
	ds_read_b128 v[138:141], v142 offset:16384
	ds_read_b128 v[146:149], v142 offset:18432
	s_waitcnt lgkmcnt(11)
	v_mfma_f32_16x16x32_bf16 v[56:59], v[98:101], v[94:97], v[56:59]
	s_lshl_b32 s33, s33, 7
	s_lshl_b32 s26, s31, 7
	s_ashr_i32 s27, s26, 31
	v_mfma_f32_16x16x32_bf16 v[60:63], v[74:77], v[94:97], v[60:63]
	s_lshl_b64 s[26:27], s[26:27], 1
	s_add_i32 s30, s30, s28
	s_cmpk_gt_i32 s30, 0xfff
	s_waitcnt lgkmcnt(0)
	v_mfma_f32_16x16x32_bf16 v[56:59], v[146:149], v[130:133], v[56:59]
	v_mfma_f32_16x16x32_bf16 v[48:51], v[110:113], v[94:97], v[48:51]
	v_mfma_f32_16x16x32_bf16 v[52:55], v[106:109], v[94:97], v[52:55]
	s_nop 5
	v_max_f32_e32 v56, v56, v56
	v_max_f32_e32 v57, v57, v57
	v_max_f32_e32 v56, 0, v56
	v_mfma_f32_16x16x32_bf16 v[44:47], v[114:117], v[94:97], v[44:47]
	v_max_f32_e32 v57, 0, v57
	v_max_f32_e32 v59, v59, v59
	v_max_f32_e32 v59, 0, v59
	v_mfma_f32_16x16x32_bf16 v[40:43], v[118:121], v[94:97], v[40:43]
	v_mfma_f32_16x16x32_bf16 v[36:39], v[122:125], v[94:97], v[36:39]
	v_mfma_f32_16x16x32_bf16 v[32:35], v[126:129], v[94:97], v[32:35]
	ds_read_b128 v[94:97], v142 offset:20480
	ds_read_b128 v[150:153], v142 offset:22528
	ds_read_b128 v[154:157], v142 offset:24576
	ds_read_b128 v[158:161], v142 offset:26624
	v_mfma_f32_16x16x32_bf16 v[60:63], v[138:141], v[130:133], v[60:63]
	s_waitcnt lgkmcnt(2)
	v_mfma_f32_16x16x32_bf16 v[48:51], v[150:153], v[130:133], v[48:51]
	v_mfma_f32_16x16x32_bf16 v[20:23], v[106:109], v[102:105], v[20:23]
	v_mul_f32_e64 v106, v56, v56
	v_mul_f32_e64 v107, v57, v57
	v_max_f32_e32 v57, v58, v58
	s_nop 1
	v_max_f32_e32 v60, v60, v60
	v_mfma_f32_16x16x32_bf16 v[24:27], v[98:101], v[102:105], v[24:27]
	v_add_u32_e32 v100, s33, v79
	v_mov_b64_e32 v[98:99], s[0:1]
	v_max_f32_e32 v61, v61, v61
	v_max_f32_e32 v56, v62, v62
	v_max_f32_e32 v58, 0, v57
	v_max_f32_e32 v57, v63, v63
	v_mad_i64_i32 v[100:101], s[34:35], v100, s29, v[98:99]
	v_max_f32_e32 v60, 0, v60
	v_max_f32_e32 v61, 0, v61
	v_max_f32_e32 v56, 0, v56
	v_max_f32_e32 v57, 0, v57
	v_mfma_f32_16x16x32_bf16 v[52:55], v[94:97], v[130:133], v[52:55]
	v_lshl_add_u64 v[100:101], v[100:101], 0, s[26:27]
	v_pk_mul_f32 v[60:61], v[60:61], v[60:61]
	v_pk_mul_f32 v[62:63], v[56:57], v[56:57]
	v_mfma_f32_16x16x32_bf16 v[28:31], v[74:77], v[102:105], v[28:31]
	v_max_f32_e32 v48, v48, v48
	v_max_f32_e32 v49, v49, v49
	ds_read_b128 v[74:77], v142 offset:28672
	ds_read_b128 v[162:165], v142 offset:30720
	v_mfma_f32_16x16x32_bf16 v[12:15], v[110:113], v[102:105], v[12:15]
	v_lshl_add_u64 v[100:101], v[100:101], 0, v[64:65]
	v_cvt_pk_bf16_f32 v56, v60, v61
	v_cvt_pk_bf16_f32 v57, v62, v63
	v_mfma_f32_16x16x32_bf16 v[8:11], v[114:117], v[102:105], v[8:11]
	v_max_f32_e32 v48, 0, v48
	v_max_f32_e32 v49, 0, v49
	v_max_f32_e32 v52, v52, v52
	v_mfma_f32_16x16x32_bf16 v[4:7], v[118:121], v[102:105], v[4:7]
	v_max_f32_e32 v53, v53, v53
	v_max_f32_e32 v51, v51, v51
	v_max_f32_e32 v52, 0, v52
	v_mfma_f32_16x16x32_bf16 v[0:3], v[122:125], v[102:105], v[0:3]
	v_max_f32_e32 v53, 0, v53
	v_max_f32_e32 v51, 0, v51
	v_pk_mul_f32 v[52:53], v[52:53], v[52:53]
	v_mfma_f32_16x16x32_bf16 v[16:19], v[126:129], v[102:105], v[16:19]
	v_mul_f32_e64 v102, v58, v58
	v_mul_f32_e64 v103, v59, v59
	v_cvt_pk_bf16_f32 v58, v106, v107
	v_cvt_pk_bf16_f32 v59, v102, v103
	s_waitcnt lgkmcnt(2)
	v_mfma_f32_16x16x32_bf16 v[40:43], v[158:161], v[130:133], v[40:43]
	global_store_dwordx4 v[100:101], v[56:59], off
	s_nop 1
	v_pk_mul_f32 v[56:57], v[48:49], v[48:49]
	v_max_f32_e32 v49, v50, v50
	v_max_f32_e32 v48, v54, v54
	v_max_f32_e32 v50, 0, v49
	v_max_f32_e32 v49, v55, v55
	v_mfma_f32_16x16x32_bf16 v[44:47], v[154:157], v[130:133], v[44:47]
	v_max_f32_e32 v48, 0, v48
	v_max_f32_e32 v49, 0, v49
	v_pk_mul_f32 v[54:55], v[48:49], v[48:49]
	v_pk_mul_f32 v[58:59], v[50:51], v[50:51]
	v_max_f32_e32 v40, v40, v40
	v_max_f32_e32 v41, v41, v41
	s_waitcnt lgkmcnt(0)
	v_mfma_f32_16x16x32_bf16 v[32:35], v[162:165], v[130:133], v[32:35]
	v_cvt_pk_bf16_f32 v48, v52, v53
	v_cvt_pk_bf16_f32 v49, v54, v55
	v_cvt_pk_bf16_f32 v50, v56, v57
	v_cvt_pk_bf16_f32 v51, v58, v59
	v_max_f32_e32 v40, 0, v40
	v_max_f32_e32 v41, 0, v41
	global_store_dwordx4 v[100:101], v[48:51], off offset:64
	v_max_f32_e32 v44, v44, v44
	v_max_f32_e32 v45, v45, v45
	v_pk_mul_f32 v[48:49], v[40:41], v[40:41]
	v_max_f32_e32 v41, v42, v42
	v_max_f32_e32 v40, v46, v46
	v_max_f32_e32 v42, 0, v41
	v_max_f32_e32 v41, v47, v47
	v_max_f32_e32 v43, v43, v43
	v_mfma_f32_16x16x32_bf16 v[36:39], v[74:77], v[130:133], v[36:39]
	v_max_f32_e32 v44, 0, v44
	v_max_f32_e32 v45, 0, v45
	v_max_f32_e32 v40, 0, v40
	v_max_f32_e32 v41, 0, v41
	v_max_f32_e32 v43, 0, v43
	v_pk_mul_f32 v[44:45], v[44:45], v[44:45]
	v_pk_mul_f32 v[46:47], v[40:41], v[40:41]
	v_pk_mul_f32 v[50:51], v[42:43], v[42:43]
	v_max_f32_e32 v32, v32, v32
	v_max_f32_e32 v33, v33, v33
	v_mfma_f32_16x16x32_bf16 v[24:27], v[146:149], v[134:137], v[24:27]
	v_cvt_pk_bf16_f32 v40, v44, v45
	v_cvt_pk_bf16_f32 v41, v46, v47
	v_cvt_pk_bf16_f32 v42, v48, v49
	v_cvt_pk_bf16_f32 v43, v50, v51
	v_max_f32_e32 v32, 0, v32
	v_max_f32_e32 v33, 0, v33
	global_store_dwordx4 v[100:101], v[40:43], off offset:128
	v_max_f32_e32 v36, v36, v36
	v_max_f32_e32 v37, v37, v37
	v_pk_mul_f32 v[40:41], v[32:33], v[32:33]
	v_max_f32_e32 v33, v34, v34
	v_max_f32_e32 v32, v38, v38
	v_max_f32_e32 v34, 0, v33
	v_max_f32_e32 v33, v39, v39
	v_max_f32_e32 v35, v35, v35
	v_mfma_f32_16x16x32_bf16 v[28:31], v[138:141], v[134:137], v[28:31]
	v_max_f32_e32 v36, 0, v36
	v_max_f32_e32 v37, 0, v37
	v_max_f32_e32 v32, 0, v32
	v_max_f32_e32 v33, 0, v33
	v_max_f32_e32 v35, 0, v35
	v_pk_mul_f32 v[36:37], v[36:37], v[36:37]
	v_pk_mul_f32 v[38:39], v[32:33], v[32:33]
	v_pk_mul_f32 v[42:43], v[34:35], v[34:35]
	v_max_f32_e32 v24, v24, v24
	v_max_f32_e32 v25, v25, v25
	v_mfma_f32_16x16x32_bf16 v[12:15], v[150:153], v[134:137], v[12:15]
	v_cvt_pk_bf16_f32 v32, v36, v37
	v_cvt_pk_bf16_f32 v33, v38, v39
	v_cvt_pk_bf16_f32 v34, v40, v41
	v_cvt_pk_bf16_f32 v35, v42, v43
	v_max_f32_e32 v24, 0, v24
	v_max_f32_e32 v25, 0, v25
	global_store_dwordx4 v[100:101], v[32:35], off offset:192
	v_max_f32_e32 v28, v28, v28
	v_max_f32_e32 v29, v29, v29
	v_pk_mul_f32 v[34:35], v[24:25], v[24:25]
	v_max_f32_e32 v25, v26, v26
	v_add_u32_e32 v32, s33, v84
	v_max_f32_e32 v24, v30, v30
	v_max_f32_e32 v26, 0, v25
	v_max_f32_e32 v25, v31, v31
	v_max_f32_e32 v27, v27, v27
	v_mfma_f32_16x16x32_bf16 v[20:23], v[94:97], v[134:137], v[20:23]
	v_mad_i64_i32 v[32:33], s[34:35], v32, s29, v[98:99]
	v_max_f32_e32 v28, 0, v28
	v_max_f32_e32 v29, 0, v29
	v_max_f32_e32 v24, 0, v24
	v_max_f32_e32 v25, 0, v25
	v_max_f32_e32 v27, 0, v27
	v_lshl_add_u64 v[32:33], v[32:33], 0, s[26:27]
	v_pk_mul_f32 v[28:29], v[28:29], v[28:29]
	v_pk_mul_f32 v[30:31], v[24:25], v[24:25]
	v_pk_mul_f32 v[36:37], v[26:27], v[26:27]
	v_max_f32_e32 v12, v12, v12
	v_max_f32_e32 v13, v13, v13
	v_mfma_f32_16x16x32_bf16 v[4:7], v[158:161], v[134:137], v[4:7]
	v_lshl_add_u64 v[32:33], v[32:33], 0, v[64:65]
	v_cvt_pk_bf16_f32 v24, v28, v29
	v_cvt_pk_bf16_f32 v25, v30, v31
	v_cvt_pk_bf16_f32 v26, v34, v35
	v_cvt_pk_bf16_f32 v27, v36, v37
	v_max_f32_e32 v12, 0, v12
	v_max_f32_e32 v13, 0, v13
	global_store_dwordx4 v[32:33], v[24:27], off
	v_max_f32_e32 v20, v20, v20
	v_max_f32_e32 v21, v21, v21
	v_pk_mul_f32 v[24:25], v[12:13], v[12:13]
	v_max_f32_e32 v13, v14, v14
	v_max_f32_e32 v12, v22, v22
	v_max_f32_e32 v14, 0, v13
	v_max_f32_e32 v13, v23, v23
	v_max_f32_e32 v15, v15, v15
	v_mfma_f32_16x16x32_bf16 v[8:11], v[154:157], v[134:137], v[8:11]
	v_max_f32_e32 v20, 0, v20
	v_max_f32_e32 v21, 0, v21
	v_max_f32_e32 v12, 0, v12
	v_max_f32_e32 v13, 0, v13
	v_max_f32_e32 v15, 0, v15
	v_pk_mul_f32 v[20:21], v[20:21], v[20:21]
	v_pk_mul_f32 v[22:23], v[12:13], v[12:13]
	v_pk_mul_f32 v[26:27], v[14:15], v[14:15]
	v_max_f32_e32 v4, v4, v4
	v_max_f32_e32 v5, v5, v5
	v_cvt_pk_bf16_f32 v12, v20, v21
	v_cvt_pk_bf16_f32 v13, v22, v23
	v_cvt_pk_bf16_f32 v14, v24, v25
	v_cvt_pk_bf16_f32 v15, v26, v27
	v_max_f32_e32 v4, 0, v4
	v_max_f32_e32 v5, 0, v5
	global_store_dwordx4 v[32:33], v[12:15], off offset:64
	v_mfma_f32_16x16x32_bf16 v[0:3], v[74:77], v[134:137], v[0:3]
	v_max_f32_e32 v8, v8, v8
	v_pk_mul_f32 v[12:13], v[4:5], v[4:5]
	v_max_f32_e32 v5, v6, v6
	v_mfma_f32_16x16x32_bf16 v[16:19], v[162:165], v[134:137], v[16:19]
	v_max_f32_e32 v9, v9, v9
	v_max_f32_e32 v4, v10, v10
	v_max_f32_e32 v6, 0, v5
	v_max_f32_e32 v5, v11, v11
	v_max_f32_e32 v7, v7, v7
	v_max_f32_e32 v8, 0, v8
	v_max_f32_e32 v9, 0, v9
	v_max_f32_e32 v4, 0, v4
	v_max_f32_e32 v5, 0, v5
	v_max_f32_e32 v7, 0, v7
	v_pk_mul_f32 v[8:9], v[8:9], v[8:9]
	v_pk_mul_f32 v[10:11], v[4:5], v[4:5]
	v_pk_mul_f32 v[14:15], v[6:7], v[6:7]
	v_cvt_pk_bf16_f32 v4, v8, v9
	v_cvt_pk_bf16_f32 v5, v10, v11
	v_cvt_pk_bf16_f32 v6, v12, v13
	v_cvt_pk_bf16_f32 v7, v14, v15
	global_store_dwordx4 v[32:33], v[4:7], off offset:128
	v_max_f32_e32 v0, v0, v0
	v_max_f32_e32 v1, v1, v1
	v_max_f32_e32 v4, v16, v16
	v_max_f32_e32 v5, v17, v17
	v_max_f32_e32 v2, v2, v2
	v_max_f32_e32 v6, v18, v18
	v_max_f32_e32 v3, v3, v3
	v_max_f32_e32 v7, v19, v19
	v_max_f32_e32 v0, 0, v0
	v_max_f32_e32 v4, 0, v4
	v_max_f32_e32 v1, 0, v1
	v_max_f32_e32 v5, 0, v5
	v_max_f32_e32 v2, 0, v2
	v_max_f32_e32 v6, 0, v6
	v_max_f32_e32 v3, 0, v3
	v_max_f32_e32 v7, 0, v7
	v_pk_mul_f32 v[0:1], v[0:1], v[0:1]
	v_pk_mul_f32 v[4:5], v[4:5], v[4:5]
	v_pk_mul_f32 v[2:3], v[2:3], v[2:3]
	v_pk_mul_f32 v[6:7], v[6:7], v[6:7]
	v_cvt_pk_bf16_f32 v0, v0, v1
	v_cvt_pk_bf16_f32 v1, v2, v3
	v_cvt_pk_bf16_f32 v2, v4, v5
	v_cvt_pk_bf16_f32 v3, v6, v7
	global_store_dwordx4 v[32:33], v[0:3], off offset:192
	s_cbranch_scc0 .LBB0_1754

.LBB0_1824:
	s_add_i32 s41, s39, 0x8000
	s_and_b32 s40, s41, 0x8000
	s_add_i32 s40, s40, 0
	s_and_b32 s39, s39, 0x8000
	s_add_i32 s39, s39, 0
	s_add_u32 s86, s39, s87
	s_waitcnt vmcnt(8)
	s_barrier
	v_add3_u32 v145, s39, v84, v85
	v_add3_u32 v178, s39, v85, v86
	v_add3_u32 v179, s39, v84, v87
	v_add3_u32 v180, s39, v86, v87
	ds_read_b128 v[104:107], v178
	ds_read_b128 v[76:79], v145 offset:16384
	ds_read_b128 v[100:103], v145 offset:18432
	ds_read_b128 v[108:111], v178 offset:2048
	ds_read_b128 v[112:115], v145 offset:20480
	ds_read_b128 v[116:119], v145 offset:22528
	ds_read_b128 v[120:123], v145 offset:24576
	ds_read_b128 v[124:127], v145 offset:26624
	ds_read_b128 v[128:131], v145 offset:28672
	ds_read_b128 v[132:135], v145 offset:30720
	ds_read_b128 v[146:149], v180
	ds_read_b128 v[136:139], v179 offset:16384
	ds_read_b128 v[140:143], v179 offset:18432
	ds_read_b128 v[150:153], v180 offset:2048
	ds_read_b128 v[154:157], v179 offset:20480
	ds_read_b128 v[158:161], v179 offset:22528
	ds_read_b128 v[162:165], v179 offset:24576
	ds_read_b128 v[166:169], v179 offset:26624
	ds_read_b128 v[170:173], v179 offset:28672
	ds_read_b128 v[174:177], v179 offset:30720
	s_waitcnt lgkmcnt(15)
	v_mfma_f32_16x16x32_bf16 v[60:63], v[76:79], v[104:107], v[60:63]
	v_mfma_f32_16x16x32_bf16 v[56:59], v[100:103], v[104:107], v[56:59]
	v_mfma_f32_16x16x32_bf16 v[24:27], v[76:79], v[108:111], v[24:27]
	v_mfma_f32_16x16x32_bf16 v[20:23], v[100:103], v[108:111], v[20:23]
	v_mfma_f32_16x16x32_bf16 v[52:55], v[112:115], v[104:107], v[52:55]
	v_mfma_f32_16x16x32_bf16 v[16:19], v[112:115], v[108:111], v[16:19]
	s_waitcnt lgkmcnt(14)
	v_mfma_f32_16x16x32_bf16 v[48:51], v[116:119], v[104:107], v[48:51]
	v_mfma_f32_16x16x32_bf16 v[12:15], v[116:119], v[108:111], v[12:15]
	s_waitcnt lgkmcnt(13)
	v_mfma_f32_16x16x32_bf16 v[44:47], v[120:123], v[104:107], v[44:47]
	v_mfma_f32_16x16x32_bf16 v[8:11], v[120:123], v[108:111], v[8:11]
	s_waitcnt lgkmcnt(12)
	v_mfma_f32_16x16x32_bf16 v[40:43], v[124:127], v[104:107], v[40:43]
	v_mfma_f32_16x16x32_bf16 v[4:7], v[124:127], v[108:111], v[4:7]
	s_waitcnt lgkmcnt(11)
	v_mfma_f32_16x16x32_bf16 v[32:35], v[128:131], v[104:107], v[32:35]
	v_mfma_f32_16x16x32_bf16 v[0:3], v[128:131], v[108:111], v[0:3]
	s_waitcnt lgkmcnt(10)
	v_mfma_f32_16x16x32_bf16 v[28:31], v[132:135], v[104:107], v[28:31]
	v_mfma_f32_16x16x32_bf16 v[36:39], v[132:135], v[108:111], v[36:39]
	s_waitcnt lgkmcnt(0)
	s_barrier
	s_cmpk_eq_i32 s28, 0x1f00
	s_cbranch_scc1 .Lgskip_1824
	s_mov_b32 m0, s86
	s_nop 0
	global_load_lds_dwordx4 v244, s[96:97]
	s_add_u32 m0, s86, 0x4000
	s_nop 0
	global_load_lds_dwordx4 v245, s[88:89]
	s_add_u32 m0, s86, 0x1000
	s_nop 0
	global_load_lds_dwordx4 v246, s[96:97]
	s_add_u32 m0, s86, 0x5000
	s_nop 0
	global_load_lds_dwordx4 v247, s[88:89]
	s_add_u32 m0, s86, 0x2000
	s_nop 0
	global_load_lds_dwordx4 v248, s[96:97]
	s_add_u32 m0, s86, 0x6000
	s_nop 0
	global_load_lds_dwordx4 v249, s[88:89]
	s_add_u32 m0, s86, 0x3000
	s_nop 0
	global_load_lds_dwordx4 v250, s[96:97]
	s_add_u32 m0, s86, 0x7000
	s_nop 0
	global_load_lds_dwordx4 v251, s[88:89]
	s_add_u32 s96, s96, 0x80
	s_addc_u32 s97, s97, 0
	s_add_u32 s88, s88, 0x80
	s_addc_u32 s89, s89, 0
.Lgskip_1824:
	s_add_u32 s28, s28, 0x80
	s_addc_u32 s29, s29, 0
	s_cmpk_eq_i32 s28, 0x1f80
	s_mov_b32 s39, s41
	v_mfma_f32_16x16x32_bf16 v[60:63], v[136:139], v[146:149], v[60:63]
	v_mfma_f32_16x16x32_bf16 v[56:59], v[140:143], v[146:149], v[56:59]
	v_mfma_f32_16x16x32_bf16 v[24:27], v[136:139], v[150:153], v[24:27]
	v_mfma_f32_16x16x32_bf16 v[20:23], v[140:143], v[150:153], v[20:23]
	v_mfma_f32_16x16x32_bf16 v[52:55], v[154:157], v[146:149], v[52:55]
	v_mfma_f32_16x16x32_bf16 v[16:19], v[154:157], v[150:153], v[16:19]
	v_mfma_f32_16x16x32_bf16 v[48:51], v[158:161], v[146:149], v[48:51]
	v_mfma_f32_16x16x32_bf16 v[12:15], v[158:161], v[150:153], v[12:15]
	v_mfma_f32_16x16x32_bf16 v[44:47], v[162:165], v[146:149], v[44:47]
	v_mfma_f32_16x16x32_bf16 v[8:11], v[162:165], v[150:153], v[8:11]
	v_mfma_f32_16x16x32_bf16 v[40:43], v[166:169], v[146:149], v[40:43]
	v_mfma_f32_16x16x32_bf16 v[4:7], v[166:169], v[150:153], v[4:7]
	v_mfma_f32_16x16x32_bf16 v[32:35], v[170:173], v[146:149], v[32:35]
	v_mfma_f32_16x16x32_bf16 v[0:3], v[170:173], v[150:153], v[0:3]
	v_mfma_f32_16x16x32_bf16 v[28:31], v[174:177], v[146:149], v[28:31]
	v_mfma_f32_16x16x32_bf16 v[36:39], v[174:177], v[150:153], v[36:39]
	s_cbranch_scc0 .LBB0_1824
	v_add_u32_e32 v80, s40, v84
	v_add_u32_e32 v81, v80, v85
	s_waitcnt vmcnt(0)
	s_barrier
	ds_read_b128 v[72:75], v81 offset:16384
	v_add3_u32 v99, s40, v85, v86
	ds_read_b128 v[76:79], v81 offset:18432
	ds_read_b128 v[100:103], v99
	ds_read_b128 v[104:107], v99 offset:2048
	ds_read_b128 v[108:111], v81 offset:20480
	ds_read_b128 v[112:115], v81 offset:22528
	ds_read_b128 v[116:119], v81 offset:24576
	ds_read_b128 v[120:123], v81 offset:26624
	ds_read_b128 v[124:127], v81 offset:28672
	ds_read_b128 v[128:131], v81 offset:30720
	v_add_u32_e32 v80, v80, v87
	s_waitcnt lgkmcnt(7)
	v_mfma_f32_16x16x32_bf16 v[60:63], v[72:75], v[100:103], v[60:63]
	s_lshl_b32 s38, s38, 7
	v_mfma_f32_16x16x32_bf16 v[56:59], v[76:79], v[100:103], v[56:59]
	s_waitcnt lgkmcnt(4)
	v_mfma_f32_16x16x32_bf16 v[48:51], v[112:115], v[100:103], v[48:51]
	s_waitcnt lgkmcnt(3)
	v_mfma_f32_16x16x32_bf16 v[44:47], v[116:119], v[100:103], v[44:47]
	s_waitcnt lgkmcnt(2)
	v_mfma_f32_16x16x32_bf16 v[40:43], v[120:123], v[100:103], v[40:43]
	s_waitcnt lgkmcnt(1)
	v_mfma_f32_16x16x32_bf16 v[32:35], v[124:127], v[100:103], v[32:35]
	s_waitcnt lgkmcnt(0)
	v_mfma_f32_16x16x32_bf16 v[28:31], v[128:131], v[100:103], v[28:31]
	v_mfma_f32_16x16x32_bf16 v[24:27], v[72:75], v[104:107], v[24:27]
	ds_read_b128 v[72:75], v80 offset:16384
	v_mfma_f32_16x16x32_bf16 v[52:55], v[108:111], v[100:103], v[52:55]
	v_mfma_f32_16x16x32_bf16 v[20:23], v[76:79], v[104:107], v[20:23]
	v_mfma_f32_16x16x32_bf16 v[16:19], v[108:111], v[104:107], v[16:19]
	v_mfma_f32_16x16x32_bf16 v[12:15], v[112:115], v[104:107], v[12:15]
	v_mfma_f32_16x16x32_bf16 v[8:11], v[116:119], v[104:107], v[8:11]
	v_mfma_f32_16x16x32_bf16 v[4:7], v[120:123], v[104:107], v[4:7]
	v_mfma_f32_16x16x32_bf16 v[0:3], v[124:127], v[104:107], v[0:3]
	v_mfma_f32_16x16x32_bf16 v[100:103], v[128:131], v[104:107], v[36:39]
	s_nop 2
	v_add3_u32 v36, s40, v87, v86
	ds_read_b128 v[76:79], v80 offset:18432
	ds_read_b128 v[104:107], v36
	ds_read_b128 v[108:111], v36 offset:2048
	ds_read_b128 v[128:131], v80 offset:28672
	ds_read_b128 v[132:135], v80 offset:30720
	ds_read_b128 v[112:115], v80 offset:20480
	ds_read_b128 v[116:119], v80 offset:22528
	ds_read_b128 v[120:123], v80 offset:24576
	ds_read_b128 v[124:127], v80 offset:26624
	s_waitcnt lgkmcnt(7)
	v_mfma_f32_16x16x32_bf16 v[60:63], v[72:75], v[104:107], v[60:63]
	s_waitcnt lgkmcnt(5)
	v_mfma_f32_16x16x32_bf16 v[36:39], v[128:131], v[104:107], v[32:35]
	s_waitcnt lgkmcnt(4)
	v_mfma_f32_16x16x32_bf16 v[32:35], v[132:135], v[104:107], v[28:31]
	v_mfma_f32_16x16x32_bf16 v[28:31], v[72:75], v[108:111], v[24:27]
	v_add_u32_e32 v72, s38, v83
	v_mul_hi_i32 v73, v72, s31
	v_mfma_f32_16x16x32_bf16 v[24:27], v[76:79], v[108:111], v[20:23]
	s_waitcnt lgkmcnt(3)
	v_mfma_f32_16x16x32_bf16 v[20:23], v[112:115], v[108:111], v[16:19]
	s_waitcnt lgkmcnt(2)
	v_mfma_f32_16x16x32_bf16 v[16:19], v[116:119], v[108:111], v[12:15]
	s_waitcnt lgkmcnt(1)
	v_mfma_f32_16x16x32_bf16 v[12:15], v[120:123], v[108:111], v[8:11]
	s_waitcnt lgkmcnt(0)
	v_mfma_f32_16x16x32_bf16 v[8:11], v[124:127], v[108:111], v[4:7]
	s_nop 2
	v_lshrrev_b32_e32 v4, 31, v73
	v_ashrrev_i32_e32 v5, 11, v73
	v_mfma_f32_16x16x32_bf16 v[56:59], v[76:79], v[104:107], v[56:59]
	v_add_u32_e32 v73, v5, v4
	v_mad_i32_i24 v78, v73, s33, v72
	v_lshlrev_b32_e32 v75, 13, v73
	v_mfma_f32_16x16x32_bf16 v[52:55], v[112:115], v[104:107], v[52:55]
	v_cmp_lt_i32_e32 vcc, s34, v78
	v_add3_u32 v74, v75, v78, s35
	v_mfma_f32_16x16x32_bf16 v[48:51], v[116:119], v[104:107], v[48:51]
	v_mfma_f32_16x16x32_bf16 v[44:47], v[120:123], v[104:107], v[44:47]
	v_mfma_f32_16x16x32_bf16 v[40:43], v[124:127], v[104:107], v[40:43]
	v_mfma_f32_16x16x32_bf16 v[4:7], v[128:131], v[108:111], v[0:3]
	v_mfma_f32_16x16x32_bf16 v[0:3], v[132:135], v[108:111], v[100:103]
	s_and_saveexec_b64 s[28:29], vcc
	s_xor_b64 s[28:29], exec, s[28:29]
	v_add3_u32 v72, v75, v78, s35
	s_or_saveexec_b64 s[28:29], s[28:29]
	v_mov_b64_e32 v[76:77], s[92:93]
	v_lshl_add_u32 v75, v73, 8, v78
	s_xor_b64 exec, exec, s[28:29]
	v_lshl_add_u32 v72, v73, 8, v78
	v_mov_b64_e32 v[76:77], s[2:3]
	s_or_b64 exec, exec, s[28:29]
	s_and_saveexec_b64 s[28:29], vcc
	s_xor_b64 s[28:29], exec, s[28:29]
	s_cbranch_execz .LBB0_1831
	v_add_u32_e32 v73, 3, v73
	v_mul_hi_i32_i24_e32 v79, 0x6000, v73
	v_mul_i32_i24_e32 v78, 0x6000, v73
	s_or_saveexec_b64 s[28:29], s[28:29]
	v_mov_b64_e32 v[80:81], s[92:93]
	s_xor_b64 exec, exec, s[28:29]
	s_cbranch_execnz .LBB0_1832
	s_branch .LBB0_1833
